# PEER expert passes restructured slice-outer: fp8 tables stored slice-major (8 column slices of 2MB) so each slice stays L2-resident; hand-written u/v passes
# speedup vs baseline: 1.1236x; 1.1236x over previous
; #define LAS __attribute__((address_space(3)))
; __global__ void __launch_bounds__(256, 2) fwd_megakernel(Params p) {
;   __shared__ __attribute__((aligned(16))) char smem[SMEM_BYTES];
;   __shared__ uint4 xb_words;
;   cg::grid_group grid = cg::this_grid();
;   if (threadIdx.x == 0) xb_words = make_uint4(0u, 0u, 0u, 0u);
;   park_params(p, smem);
;   XcdBarrier xb = xcd_barrier_post((unsigned*)(p.ws + OFF_BAR), (volatile LAS unsigned*)&xb_words);
_Z14fwd_megakernel6Params:
	s_mov_b32 m0, 0
	s_load_dwordx4 s[84:87], s[0:1], 0xe0
	s_load_dwordx8 s[36:43], s[0:1], 0xc0
	s_mov_b32 s51, s2
	s_add_u32 s2, s0, 0xe8
	s_addc_u32 s3, s1, 0
	v_and_b32_e32 v195, 0x3ff, v0
	v_writelane_b32 v252, s2, 0
	v_cmp_eq_u32_e64 s[90:91], 0, v195
	s_nop 0
	v_writelane_b32 v252, s3, 1
	s_and_saveexec_b64 s[2:3], s[90:91]
	s_cbranch_execz .LBB0_2
	v_mov_b32_e32 v2, 0
	v_mov_b32_e32 v3, v2
	v_mov_b32_e32 v4, v2
	v_mov_b32_e32 v5, v2
	v_mov_b32_e32 v1, 0x13c00
	ds_write_b128 v1, v[2:5]

; __global__ void __launch_bounds__(256, 2) fwd_megakernel(Params p) {
;     ...
; #pragma unroll 1
;   for (int ph = 0; ph < NPHASE; ph++) {
;     if (ph == 11) continue;
;     if (ph == 10 || ph == 20) { run_phase(ph + 100, smem); xcd_barrier(xb); }
;     run_phase(ph, smem);
;     if (ph + 1 < NPHASE) xcd_barrier(xb);
;     if (p.ws == nullptr) grid.sync();
;   }
.LBB0_10:
	s_cmp_eq_u32 s57, 10
	s_cbranch_scc1 .Lpeer_adv
	s_cmp_eq_u32 s57, 20
	s_cbranch_scc0 .Lphase_adv
.Lpeer_adv:
	s_cmp_eq_u32 m0, 0
	s_cbranch_scc0 .Lphase_adv0
	s_mov_b32 m0, 1
	s_branch .LBB0_11
.Lphase_adv0:
	s_mov_b32 m0, 0

; DEV void run_phase(int ph, char* smem) {
;     ...
;   switch (ph) {
;     case 0: phase_prep(p, smem); break;
;     case 1: phase_norm(p, 0, 0, MT, true); break;
;     case 2: phase_gemm_win(p, smem); break;
;     case 3: phase_post1(p); break;
;     case 4: phase_qkv_conv(p, smem); break;
;     case 5: phase_attn(p, smem); break;
;     case 6: phase_gemm_out(p, 0, smem); break;
;     case 7: phase_norm(p, 0, 1, MT, false); break;
;     case 8: phase_gemm_pq(p, 0, MT, smem); break;
;     case 9: phase_peer_score(p, 0, MT, smem); break;
;     case 10: phase_peer_expert(p, 0, MT, false, 1, smem); break;
;     case 110: phase_peer_expert(p, 0, MT, false, 0, smem); break;
;     case 11: break;
;     case 12: phase_gemm_hgin(p, smem); break;
;     case 13: phase_hg_c1(p, smem); break;
;     case 14: phase_hg_c2(p); break;
;     case 15: phase_hg_c3(p, smem); break;
;     case 16: phase_gemm_out(p, 1, smem); break;
;     case 17: phase_norm(p, 1, 1, MM, false); break;
;     case 18: phase_gemm_pq(p, 1, MM, smem); break;
;     case 19: phase_peer_score(p, 1, MM, smem); break;
;     case 20: phase_peer_expert(p, 1, MM, true, 1, smem); break;
;     case 120: phase_peer_expert(p, 1, MM, true, 0, smem); break;
;     default: break;
;   }
.LBB0_11:
	s_cmp_eq_u32 s57, 10
	s_cbranch_scc1 .Lpeer_entry
	s_cmp_eq_u32 s57, 20
	s_cbranch_scc1 .Lpeer_entry
	s_cmp_lt_i32 s57, 11
	s_cbranch_scc1 .LBB0_14
	s_cmp_gt_i32 s57, 19
	s_cbranch_scc0 .LBB0_15
	s_cmp_eq_u32 s57, 20
	s_mov_b64 s[0:1], -1
	s_cselect_b64 s[2:3], -1, 0
	s_cbranch_execz .LBB0_16
	s_branch .LBB0_17

; DEV int tidx() { int t = threadIdx.x; asm volatile("" : "+v"(t)); return t; }
; DEV void phase_peer_expert(const Params& p, int layer, int M, bool final_, int part, char* smem) {
;   const bf16_t* H = WSP(bf16_t, OFF_H);
;   const int* EIDX = layer ? WSP(int, L1_EIDX) : WSP(int, R_EIDX);
;   const float* GATE = layer ? WSP(float, L1_GATE) : WSP(float, R_GATE);
;   const float* USEL = GATE + (size_t)MT * 128;
;   const unsigned char* U = layer ? WSP(unsigned char, OFF_U1) : WSP(unsigned char, OFF_U0);
;   const unsigned char* V = layer ? WSP(unsigned char, OFF_V1) : WSP(unsigned char, OFF_V0);
;   float* X = WSP(float, OFF_X);
;   float* COEF = layer ? WSP(float, L1_COEF) : WSP(float, R_COEF);
;   const float* mod = WSP(float, S_MOD) + (size_t)layer * 3 * 6144;
;   const int tid = tidx(), lane = tid & 63, w = tid >> 6, g = lane >> 4, l16 = lane & 15;
;   int* se = (int*)smem + w * 512;
;   float* sg = (float*)(se + 128);
;   float* su = sg + 128;
;   float* coefs = su + 128;
;   if (part == 0) {
;   for (int m = blockIdx.x * 4 + w; m < M; m += gridDim.x * 4) {
;     {
;       int2 e2 = *(const int2*)(EIDX + (size_t)m * 128 + lane * 2);
;       float2 g2 = *(const float2*)(GATE + (size_t)m * 128 + lane * 2);
;       float2 u2 = *(const float2*)(USEL + (size_t)m * 128 + lane * 2);
;       *(int2*)(se + lane * 2) = e2; *(float2*)(sg + lane * 2) = g2; *(float2*)(su + lane * 2) = u2;
.Lpeer_entry:
	s_mov_b64 exec, -1
	v_mov_b32_e32 v2, 0x13bd8
	ds_read_b64 v[2:3], v2
	v_lshrrev_b32_e32 v4, 6, v195
	v_and_b32_e32 v162, 63, v195
	v_and_b32_e32 v163, 7, v195
	v_bfe_u32 v164, v195, 3, 3
	v_lshlrev_b32_e32 v156, 4, v163
	s_waitcnt lgkmcnt(0)
	v_readfirstlane_b32 s0, v2
	v_readfirstlane_b32 s1, v3
	v_readfirstlane_b32 s6, v4
	s_mov_b32 s7, 32
	s_mov_b32 s8, 8
	s_mov_b32 s40, 0x10500000
	s_mov_b32 s41, 0x6700000
	s_mov_b32 s42, 0x10e00000
	s_mov_b32 s43, 0x11f00000
	s_mov_b32 s45, 0x8300000
	s_mov_b32 s52, 0xbf57000
	s_cmp_lg_u32 s57, 10
	s_cbranch_scc1 .Lpeer_l1
	s_mov_b32 s7, 33
	s_mov_b32 s40, 0x1bb00000
	s_mov_b32 s41, 0xc300000
	s_mov_b32 s42, 0x1c400000
	s_mov_b32 s43, 0x1d500000
	s_mov_b32 s45, 0xe300000
	s_mov_b32 s52, 0xbf45000
	s_cmp_lg_u32 s6, 0
	s_cbranch_scc1 .Lpeer_l1
	s_mov_b32 s8, 9
.Lpeer_l1:
	s_mul_i32 s9, s51, s7
	s_add_u32 s9, s9, s6
	s_add_u32 s10, s0, s40
	s_addc_u32 s11, s1, 0
	s_mul_i32 s44, s6, 0x1200
	v_lshl_add_u32 v157, v164, 6, s44
	v_lshl_add_u32 v165, v163, 3, v164
	v_lshlrev_b32_e32 v165, 2, v165
	s_lshl_b32 s2, s9, 9
	v_lshl_add_u32 v166, v162, 3, s2
	v_and_b32_e32 v159, 3, v162
	v_lshlrev_b32_e32 v159, 7, v159
	v_lshrrev_b32_e32 v160, 2, v162
	v_lshl_add_u32 v167, v160, 2, v159
	v_add_u32_e32 v167, s44, v167
	v_add_u32_e32 v159, 0, v166
	global_load_dwordx2 v[2:3], v159, s[10:11]
	v_add_u32_e32 v159, 2048, v166
	global_load_dwordx2 v[4:5], v159, s[10:11]
	v_add_u32_e32 v159, 4096, v166
	global_load_dwordx2 v[6:7], v159, s[10:11]
	v_add_u32_e32 v159, 6144, v166
	global_load_dwordx2 v[8:9], v159, s[10:11]
	v_add_u32_e32 v159, 8192, v166
	global_load_dwordx2 v[10:11], v159, s[10:11]
	v_add_u32_e32 v159, 10240, v166
	global_load_dwordx2 v[12:13], v159, s[10:11]
	v_add_u32_e32 v159, 12288, v166
	global_load_dwordx2 v[14:15], v159, s[10:11]
	v_add_u32_e32 v159, 14336, v166
	global_load_dwordx2 v[16:17], v159, s[10:11]
	v_add_u32_e32 v159, 16384, v166
	global_load_dwordx2 v[18:19], v159, s[10:11]
	s_waitcnt vmcnt(0)
	v_lshlrev_b32_e32 v2, 7, v2
	v_lshlrev_b32_e32 v3, 7, v3
	ds_write_b32 v167, v2 offset:0
	ds_write_b32 v167, v3 offset:64
	v_lshlrev_b32_e32 v4, 7, v4
	v_lshlrev_b32_e32 v5, 7, v5
	ds_write_b32 v167, v4 offset:512
	ds_write_b32 v167, v5 offset:576
	v_lshlrev_b32_e32 v6, 7, v6
	v_lshlrev_b32_e32 v7, 7, v7
	ds_write_b32 v167, v6 offset:1024
	ds_write_b32 v167, v7 offset:1088
	v_lshlrev_b32_e32 v8, 7, v8
	v_lshlrev_b32_e32 v9, 7, v9
	ds_write_b32 v167, v8 offset:1536
	ds_write_b32 v167, v9 offset:1600
	v_lshlrev_b32_e32 v10, 7, v10
	v_lshlrev_b32_e32 v11, 7, v11
	ds_write_b32 v167, v10 offset:2048
	ds_write_b32 v167, v11 offset:2112
	v_lshlrev_b32_e32 v12, 7, v12
	v_lshlrev_b32_e32 v13, 7, v13
	ds_write_b32 v167, v12 offset:2560
	ds_write_b32 v167, v13 offset:2624
	v_lshlrev_b32_e32 v14, 7, v14
	v_lshlrev_b32_e32 v15, 7, v15
	ds_write_b32 v167, v14 offset:3072
	ds_write_b32 v167, v15 offset:3136
	v_lshlrev_b32_e32 v16, 7, v16
	v_lshlrev_b32_e32 v17, 7, v17
	ds_write_b32 v167, v16 offset:3584
	ds_write_b32 v167, v17 offset:3648
	v_lshlrev_b32_e32 v18, 7, v18
	v_lshlrev_b32_e32 v19, 7, v19
	ds_write_b32 v167, v18 offset:4096
	ds_write_b32 v167, v19 offset:4160
	s_cmp_eq_u32 m0, 0
	s_cbranch_scc0 .Lpeer_v
.Lpeer_u:
	s_add_u32 s12, s0, 0x4200000
	s_addc_u32 s13, s1, 0
	s_add_u32 s14, s0, s41
	s_addc_u32 s15, s1, 0
	s_add_u32 s16, s0, s42
	s_addc_u32 s17, s1, 0
	s_add_u32 s2, s0, s43
	s_addc_u32 s3, s1, 0
	s_add_u32 s45, s44, 0x4800
	v_add_u32_e32 v161, s45, v165
	v_cmp_eq_u32_e32 vcc, 0, v163
	s_nop 1
	v_cndmask_b32_e64 v148, 0, 1.0, vcc
	v_cmp_eq_u32_e32 vcc, 1, v163
	s_nop 1
	v_cndmask_b32_e64 v149, 0, 1.0, vcc
	v_cmp_eq_u32_e32 vcc, 2, v163
	s_nop 1
	v_cndmask_b32_e64 v150, 0, 1.0, vcc
	v_cmp_eq_u32_e32 vcc, 3, v163
	s_nop 1
	v_cndmask_b32_e64 v151, 0, 1.0, vcc
	v_cmp_eq_u32_e32 vcc, 4, v163
	s_nop 1
	v_cndmask_b32_e64 v152, 0, 1.0, vcc
	v_cmp_eq_u32_e32 vcc, 5, v163
	s_nop 1
	v_cndmask_b32_e64 v153, 0, 1.0, vcc
	v_cmp_eq_u32_e32 vcc, 6, v163
	s_nop 1
	v_cndmask_b32_e64 v154, 0, 1.0, vcc
	v_cmp_eq_u32_e32 vcc, 7, v163
	s_nop 1
	v_cndmask_b32_e64 v155, 0, 1.0, vcc
	s_mul_i32 s40, s9, 0x880
	v_lshl_add_u32 v158, v163, 5, s40
	v_mov_b32_e32 v160, 0
	ds_write_b32 v161, v160 offset:0
	ds_write_b32 v161, v160 offset:256
	ds_write_b32 v161, v160 offset:512
	ds_write_b32 v161, v160 offset:768
	ds_write_b32 v161, v160 offset:1024
	ds_write_b32 v161, v160 offset:1280
	ds_write_b32 v161, v160 offset:1536
	ds_write_b32 v161, v160 offset:1792
	ds_write_b32 v161, v160 offset:2048
	ds_write_b32 v161, v160 offset:2304
	ds_write_b32 v161, v160 offset:2560
	ds_write_b32 v161, v160 offset:2816
	ds_write_b32 v161, v160 offset:3072
	ds_write_b32 v161, v160 offset:3328
	ds_write_b32 v161, v160 offset:3584
	ds_write_b32 v161, v160 offset:3840
	ds_write_b32 v161, v160 offset:4096
	ds_write_b32 v161, v160 offset:4352
	s_mov_b32 s18, 0
	s_mov_b32 s20, 0
	global_load_dwordx4 v[82:85], v158, s[12:13]
	global_load_dwordx4 v[86:89], v158, s[12:13] offset:16
	s_waitcnt lgkmcnt(0)
	ds_read_b128 v[66:69], v157 offset:0
	ds_read_b128 v[70:73], v157 offset:16
	ds_read_b128 v[74:77], v157 offset:32
	ds_read_b128 v[78:81], v157 offset:48
	s_waitcnt vmcnt(0) lgkmcnt(0)
; DEV f32x2 fp8dot4(unsigned u, f32x2 xa, f32x2 xb, f32x2 d) {
;   d += __builtin_amdgcn_cvt_pk_f32_fp8((int)u, false) * xa;
;   d += __builtin_amdgcn_cvt_pk_f32_fp8((int)u, true) * xb;
;   return d;
; }
; DEV void phase_peer_expert(const Params& p, int layer, int M, bool final_, int part, char* smem) {
;     ...
;     const bf16_t* hrow = H + (size_t)m * LDH + l16 * 16;
;     f32x2 xf[32];
; #pragma unroll
;     for (int c = 0; c < 4; c++) {
;       uint4 a = *(const uint4*)(hrow + c * 256), bq = *(const uint4*)(hrow + c * 256 + 8);
;       xf[c * 8 + 0] = (f32x2){bflo(a.x), bfhi(a.x)}; xf[c * 8 + 1] = (f32x2){bflo(a.y), bfhi(a.y)};
;       xf[c * 8 + 2] = (f32x2){bflo(a.z), bfhi(a.z)}; xf[c * 8 + 3] = (f32x2){bflo(a.w), bfhi(a.w)};
;       xf[c * 8 + 4] = (f32x2){bflo(bq.x), bfhi(bq.x)}; xf[c * 8 + 5] = (f32x2){bflo(bq.y), bfhi(bq.y)};
;       xf[c * 8 + 6] = (f32x2){bflo(bq.z), bfhi(bq.z)}; xf[c * 8 + 7] = (f32x2){bflo(bq.w), bfhi(bq.w)};
;     }
;     __syncthreads();
;     u32x4 cur[8], nxt[8];
;     {
;       const unsigned char* r0p = U + (size_t)se[g] * 1024 + l16 * 16;
;       const unsigned char* r1p = U + (size_t)se[4 + g] * 1024 + l16 * 16;
; #pragma unroll
;       for (int c = 0; c < 4; c++) { cur[c] = *(const u32x4*)(r0p + c * 256); cur[4 + c] = *(const u32x4*)(r1p + c * 256); }
;     }
; #pragma unroll 2
;     for (int st = 0; st < 16; st++) {
;       if (st + 1 < 16) {
;         const unsigned char* r0p = U + (size_t)se[(st + 1) * 8 + g] * 1024 + l16 * 16;
;         const unsigned char* r1p = U + (size_t)se[(st + 1) * 8 + 4 + g] * 1024 + l16 * 16;
; #pragma unroll
;         for (int c = 0; c < 4; c++) { nxt[c] = *(const u32x4*)(r0p + c * 256); nxt[4 + c] = *(const u32x4*)(r1p + c * 256); }
;       }
;       f32x2 da = (f32x2){0.f, 0.f}, db = (f32x2){0.f, 0.f};
; #pragma unroll
;       for (int c = 0; c < 4; c++) {
;         da = fp8dot4(cur[c][0], xf[c * 8 + 0], xf[c * 8 + 1], da); da = fp8dot4(cur[c][1], xf[c * 8 + 2], xf[c * 8 + 3], da);
;         da = fp8dot4(cur[c][2], xf[c * 8 + 4], xf[c * 8 + 5], da); da = fp8dot4(cur[c][3], xf[c * 8 + 6], xf[c * 8 + 7], da);
;         db = fp8dot4(cur[4 + c][0], xf[c * 8 + 0], xf[c * 8 + 1], db); db = fp8dot4(cur[4 + c][1], xf[c * 8 + 2], xf[c * 8 + 3], db);
;         db = fp8dot4(cur[4 + c][2], xf[c * 8 + 4], xf[c * 8 + 5], db); db = fp8dot4(cur[4 + c][3], xf[c * 8 + 6], xf[c * 8 + 7], db);
;       }
	v_lshlrev_b32_e32 v90, 16, v82
	v_and_b32_e32 v91, 0xffff0000, v82
	v_lshlrev_b32_e32 v92, 16, v83
	v_and_b32_e32 v93, 0xffff0000, v83
	v_lshlrev_b32_e32 v94, 16, v84
	v_and_b32_e32 v95, 0xffff0000, v84
	v_lshlrev_b32_e32 v96, 16, v85
	v_and_b32_e32 v97, 0xffff0000, v85
	v_lshlrev_b32_e32 v98, 16, v86
	v_and_b32_e32 v99, 0xffff0000, v86
	v_lshlrev_b32_e32 v100, 16, v87
	v_and_b32_e32 v101, 0xffff0000, v87
	v_lshlrev_b32_e32 v102, 16, v88
	v_and_b32_e32 v103, 0xffff0000, v88
	v_lshlrev_b32_e32 v104, 16, v89
	v_and_b32_e32 v105, 0xffff0000, v89
	v_add_u32_e32 v159, v66, v156
	global_load_dwordx4 v[2:5], v159, s[14:15]
	v_add_u32_e32 v159, v67, v156
	global_load_dwordx4 v[6:9], v159, s[14:15]
	v_add_u32_e32 v159, v68, v156
	global_load_dwordx4 v[10:13], v159, s[14:15]
	v_add_u32_e32 v159, v69, v156
	global_load_dwordx4 v[14:17], v159, s[14:15]
	v_add_u32_e32 v159, v70, v156
	global_load_dwordx4 v[18:21], v159, s[14:15]
	v_add_u32_e32 v159, v71, v156
	global_load_dwordx4 v[22:25], v159, s[14:15]
	v_add_u32_e32 v159, v72, v156
	global_load_dwordx4 v[26:29], v159, s[14:15]
	v_add_u32_e32 v159, v73, v156
	global_load_dwordx4 v[30:33], v159, s[14:15]
	v_add_u32_e32 v159, v74, v156
	global_load_dwordx4 v[34:37], v159, s[14:15]
	v_add_u32_e32 v159, v75, v156
	global_load_dwordx4 v[38:41], v159, s[14:15]
	v_add_u32_e32 v159, v76, v156
	global_load_dwordx4 v[42:45], v159, s[14:15]
	v_add_u32_e32 v159, v77, v156
	global_load_dwordx4 v[46:49], v159, s[14:15]
	v_add_u32_e32 v159, v78, v156
	global_load_dwordx4 v[50:53], v159, s[14:15]
	v_add_u32_e32 v159, v79, v156
	global_load_dwordx4 v[54:57], v159, s[14:15]
	v_add_u32_e32 v159, v80, v156
	global_load_dwordx4 v[58:61], v159, s[14:15]
	v_add_u32_e32 v159, v81, v156
	global_load_dwordx4 v[62:65], v159, s[14:15]
	s_mov_b32 s22, 1
	s_mov_b32 s28, 0
	s_mov_b32 s29, 0x2200
	s_lshl_b32 s40, s28, 21
	s_add_u32 s38, s14, s40
	s_addc_u32 s39, s15, 0
	s_lshl_b32 s32, s22, 9
	s_lshl_b32 s37, s8, 3
.Lu_loop:
	v_add_u32_e32 v159, s29, v158
	global_load_dwordx4 v[82:85], v159, s[12:13]
	global_load_dwordx4 v[86:89], v159, s[12:13] offset:16
	v_add_u32_e32 v160, s32, v157
	ds_read_b128 v[66:69], v160 offset:0
	ds_read_b128 v[70:73], v160 offset:16
	ds_read_b128 v[74:77], v160 offset:32
	ds_read_b128 v[78:81], v160 offset:48
	v_mov_b32_e32 v146, 0
	v_mov_b32_e32 v147, 0
	s_waitcnt vmcnt(10)
	v_cvt_pk_f32_fp8_e32 v[122:123], v2
	v_cvt_pk_f32_fp8_e32 v[126:127], v6
	v_cvt_pk_f32_fp8_sdwa v[124:125], v2 src0_sel:WORD_1
	v_cvt_pk_f32_fp8_sdwa v[128:129], v6 src0_sel:WORD_1
	v_pk_fma_f32 v[106:107], v[122:123], v[90:91], 0 op_sel_hi:[1,1,0]
	v_pk_fma_f32 v[108:109], v[126:127], v[90:91], 0 op_sel_hi:[1,1,0]
	v_pk_fma_f32 v[106:107], v[124:125], v[92:93], v[106:107]
	v_pk_fma_f32 v[108:109], v[128:129], v[92:93], v[108:109]
	v_cvt_pk_f32_fp8_e32 v[122:123], v3
	v_cvt_pk_f32_fp8_e32 v[126:127], v7
	v_cvt_pk_f32_fp8_sdwa v[124:125], v3 src0_sel:WORD_1
	v_cvt_pk_f32_fp8_sdwa v[128:129], v7 src0_sel:WORD_1
	v_pk_fma_f32 v[106:107], v[122:123], v[94:95], v[106:107]
	v_pk_fma_f32 v[108:109], v[126:127], v[94:95], v[108:109]
	v_pk_fma_f32 v[106:107], v[124:125], v[96:97], v[106:107]
	v_pk_fma_f32 v[108:109], v[128:129], v[96:97], v[108:109]
	v_cvt_pk_f32_fp8_e32 v[122:123], v4
	v_cvt_pk_f32_fp8_e32 v[126:127], v8
	v_cvt_pk_f32_fp8_sdwa v[124:125], v4 src0_sel:WORD_1
	v_cvt_pk_f32_fp8_sdwa v[128:129], v8 src0_sel:WORD_1
	v_pk_fma_f32 v[106:107], v[122:123], v[98:99], v[106:107]
	v_pk_fma_f32 v[108:109], v[126:127], v[98:99], v[108:109]
	v_pk_fma_f32 v[106:107], v[124:125], v[100:101], v[106:107]
	v_pk_fma_f32 v[108:109], v[128:129], v[100:101], v[108:109]
	v_cvt_pk_f32_fp8_e32 v[122:123], v5
	v_cvt_pk_f32_fp8_e32 v[126:127], v9
	v_cvt_pk_f32_fp8_sdwa v[124:125], v5 src0_sel:WORD_1
	v_cvt_pk_f32_fp8_sdwa v[128:129], v9 src0_sel:WORD_1
	v_pk_fma_f32 v[106:107], v[122:123], v[102:103], v[106:107]
	v_pk_fma_f32 v[108:109], v[126:127], v[102:103], v[108:109]
	v_pk_fma_f32 v[106:107], v[124:125], v[104:105], v[106:107]
	v_pk_fma_f32 v[108:109], v[128:129], v[104:105], v[108:109]
	v_cvt_pk_f32_fp8_e32 v[122:123], v10
	v_cvt_pk_f32_fp8_e32 v[126:127], v14
	v_cvt_pk_f32_fp8_sdwa v[124:125], v10 src0_sel:WORD_1
	v_cvt_pk_f32_fp8_sdwa v[128:129], v14 src0_sel:WORD_1
	v_pk_fma_f32 v[110:111], v[122:123], v[90:91], 0 op_sel_hi:[1,1,0]
	v_pk_fma_f32 v[112:113], v[126:127], v[90:91], 0 op_sel_hi:[1,1,0]
	v_pk_fma_f32 v[110:111], v[124:125], v[92:93], v[110:111]
	v_pk_fma_f32 v[112:113], v[128:129], v[92:93], v[112:113]
	v_cvt_pk_f32_fp8_e32 v[122:123], v11
	v_cvt_pk_f32_fp8_e32 v[126:127], v15
	v_cvt_pk_f32_fp8_sdwa v[124:125], v11 src0_sel:WORD_1
	v_cvt_pk_f32_fp8_sdwa v[128:129], v15 src0_sel:WORD_1
	v_pk_fma_f32 v[110:111], v[122:123], v[94:95], v[110:111]
	v_pk_fma_f32 v[112:113], v[126:127], v[94:95], v[112:113]
	v_pk_fma_f32 v[110:111], v[124:125], v[96:97], v[110:111]
	v_pk_fma_f32 v[112:113], v[128:129], v[96:97], v[112:113]
	v_cvt_pk_f32_fp8_e32 v[122:123], v12
	v_cvt_pk_f32_fp8_e32 v[126:127], v16
	v_cvt_pk_f32_fp8_sdwa v[124:125], v12 src0_sel:WORD_1
	v_cvt_pk_f32_fp8_sdwa v[128:129], v16 src0_sel:WORD_1
	v_pk_fma_f32 v[110:111], v[122:123], v[98:99], v[110:111]
	v_pk_fma_f32 v[112:113], v[126:127], v[98:99], v[112:113]
	v_pk_fma_f32 v[110:111], v[124:125], v[100:101], v[110:111]
	v_pk_fma_f32 v[112:113], v[128:129], v[100:101], v[112:113]
	v_cvt_pk_f32_fp8_e32 v[122:123], v13
	v_cvt_pk_f32_fp8_e32 v[126:127], v17
	v_cvt_pk_f32_fp8_sdwa v[124:125], v13 src0_sel:WORD_1
	v_cvt_pk_f32_fp8_sdwa v[128:129], v17 src0_sel:WORD_1
	v_pk_fma_f32 v[110:111], v[122:123], v[102:103], v[110:111]
	v_pk_fma_f32 v[112:113], v[126:127], v[102:103], v[112:113]
; DEV void phase_peer_expert(const Params& p, int layer, int M, bool final_, int part, char* smem) {
;     ...
;       f32x2 da = (f32x2){0.f, 0.f}, db = (f32x2){0.f, 0.f};
; #pragma unroll
;       for (int c = 0; c < 4; c++) {
;         da = fp8dot4(cur[c][0], xf[c * 8 + 0], xf[c * 8 + 1], da); da = fp8dot4(cur[c][1], xf[c * 8 + 2], xf[c * 8 + 3], da);
;         da = fp8dot4(cur[c][2], xf[c * 8 + 4], xf[c * 8 + 5], da); da = fp8dot4(cur[c][3], xf[c * 8 + 6], xf[c * 8 + 7], da);
;         db = fp8dot4(cur[4 + c][0], xf[c * 8 + 0], xf[c * 8 + 1], db); db = fp8dot4(cur[4 + c][1], xf[c * 8 + 2], xf[c * 8 + 3], db);
;         db = fp8dot4(cur[4 + c][2], xf[c * 8 + 4], xf[c * 8 + 5], db); db = fp8dot4(cur[4 + c][3], xf[c * 8 + 6], xf[c * 8 + 7], db);
;       }
;       float d0 = da.x + da.y, d1 = db.x + db.y;
;       d0 += __shfl_xor(d0, 1); d1 += __shfl_xor(d1, 1);
;       d0 += __shfl_xor(d0, 2); d1 += __shfl_xor(d1, 2);
;       d0 += __shfl_xor(d0, 4); d1 += __shfl_xor(d1, 4);
;       d0 += __shfl_xor(d0, 8); d1 += __shfl_xor(d1, 8);
	v_pk_fma_f32 v[110:111], v[124:125], v[104:105], v[110:111]
	v_pk_fma_f32 v[112:113], v[128:129], v[104:105], v[112:113]
	v_cvt_pk_f32_fp8_e32 v[122:123], v18
	v_cvt_pk_f32_fp8_e32 v[126:127], v22
	v_cvt_pk_f32_fp8_sdwa v[124:125], v18 src0_sel:WORD_1
	v_cvt_pk_f32_fp8_sdwa v[128:129], v22 src0_sel:WORD_1
	v_pk_fma_f32 v[114:115], v[122:123], v[90:91], 0 op_sel_hi:[1,1,0]
	v_pk_fma_f32 v[116:117], v[126:127], v[90:91], 0 op_sel_hi:[1,1,0]
	v_pk_fma_f32 v[114:115], v[124:125], v[92:93], v[114:115]
	v_pk_fma_f32 v[116:117], v[128:129], v[92:93], v[116:117]
	v_cvt_pk_f32_fp8_e32 v[122:123], v19
	v_cvt_pk_f32_fp8_e32 v[126:127], v23
	v_cvt_pk_f32_fp8_sdwa v[124:125], v19 src0_sel:WORD_1
	v_cvt_pk_f32_fp8_sdwa v[128:129], v23 src0_sel:WORD_1
	v_pk_fma_f32 v[114:115], v[122:123], v[94:95], v[114:115]
	v_pk_fma_f32 v[116:117], v[126:127], v[94:95], v[116:117]
	v_pk_fma_f32 v[114:115], v[124:125], v[96:97], v[114:115]
	v_pk_fma_f32 v[116:117], v[128:129], v[96:97], v[116:117]
	v_cvt_pk_f32_fp8_e32 v[122:123], v20
	v_cvt_pk_f32_fp8_e32 v[126:127], v24
	v_cvt_pk_f32_fp8_sdwa v[124:125], v20 src0_sel:WORD_1
	v_cvt_pk_f32_fp8_sdwa v[128:129], v24 src0_sel:WORD_1
	v_pk_fma_f32 v[114:115], v[122:123], v[98:99], v[114:115]
	v_pk_fma_f32 v[116:117], v[126:127], v[98:99], v[116:117]
	v_pk_fma_f32 v[114:115], v[124:125], v[100:101], v[114:115]
	v_pk_fma_f32 v[116:117], v[128:129], v[100:101], v[116:117]
	v_cvt_pk_f32_fp8_e32 v[122:123], v21
	v_cvt_pk_f32_fp8_e32 v[126:127], v25
	v_cvt_pk_f32_fp8_sdwa v[124:125], v21 src0_sel:WORD_1
	v_cvt_pk_f32_fp8_sdwa v[128:129], v25 src0_sel:WORD_1
	v_pk_fma_f32 v[114:115], v[122:123], v[102:103], v[114:115]
	v_pk_fma_f32 v[116:117], v[126:127], v[102:103], v[116:117]
	v_pk_fma_f32 v[114:115], v[124:125], v[104:105], v[114:115]
	v_pk_fma_f32 v[116:117], v[128:129], v[104:105], v[116:117]
	v_cvt_pk_f32_fp8_e32 v[122:123], v26
	v_cvt_pk_f32_fp8_e32 v[126:127], v30
	v_cvt_pk_f32_fp8_sdwa v[124:125], v26 src0_sel:WORD_1
	v_cvt_pk_f32_fp8_sdwa v[128:129], v30 src0_sel:WORD_1
	v_pk_fma_f32 v[118:119], v[122:123], v[90:91], 0 op_sel_hi:[1,1,0]
	v_pk_fma_f32 v[120:121], v[126:127], v[90:91], 0 op_sel_hi:[1,1,0]
	v_pk_fma_f32 v[118:119], v[124:125], v[92:93], v[118:119]
	v_pk_fma_f32 v[120:121], v[128:129], v[92:93], v[120:121]
	v_cvt_pk_f32_fp8_e32 v[122:123], v27
	v_cvt_pk_f32_fp8_e32 v[126:127], v31
	v_cvt_pk_f32_fp8_sdwa v[124:125], v27 src0_sel:WORD_1
	v_cvt_pk_f32_fp8_sdwa v[128:129], v31 src0_sel:WORD_1
	v_pk_fma_f32 v[118:119], v[122:123], v[94:95], v[118:119]
	v_pk_fma_f32 v[120:121], v[126:127], v[94:95], v[120:121]
	v_pk_fma_f32 v[118:119], v[124:125], v[96:97], v[118:119]
	v_pk_fma_f32 v[120:121], v[128:129], v[96:97], v[120:121]
	v_cvt_pk_f32_fp8_e32 v[122:123], v28
	v_cvt_pk_f32_fp8_e32 v[126:127], v32
	v_cvt_pk_f32_fp8_sdwa v[124:125], v28 src0_sel:WORD_1
	v_cvt_pk_f32_fp8_sdwa v[128:129], v32 src0_sel:WORD_1
	v_pk_fma_f32 v[118:119], v[122:123], v[98:99], v[118:119]
	v_pk_fma_f32 v[120:121], v[126:127], v[98:99], v[120:121]
	v_pk_fma_f32 v[118:119], v[124:125], v[100:101], v[118:119]
	v_pk_fma_f32 v[120:121], v[128:129], v[100:101], v[120:121]
	v_cvt_pk_f32_fp8_e32 v[122:123], v29
	v_cvt_pk_f32_fp8_e32 v[126:127], v33
	v_cvt_pk_f32_fp8_sdwa v[124:125], v29 src0_sel:WORD_1
	v_cvt_pk_f32_fp8_sdwa v[128:129], v33 src0_sel:WORD_1
	v_pk_fma_f32 v[118:119], v[122:123], v[102:103], v[118:119]
	v_pk_fma_f32 v[120:121], v[126:127], v[102:103], v[120:121]
	v_pk_fma_f32 v[118:119], v[124:125], v[104:105], v[118:119]
	v_pk_fma_f32 v[120:121], v[128:129], v[104:105], v[120:121]
	s_nop 0
	v_add_f32_e32 v138, v106, v107
	v_add_f32_e32 v139, v108, v109
	v_add_f32_e32 v140, v110, v111
	v_add_f32_e32 v141, v112, v113
	v_add_f32_e32 v142, v114, v115
	v_add_f32_e32 v143, v116, v117
	v_add_f32_e32 v144, v118, v119
	v_add_f32_e32 v145, v120, v121
	s_nop 1
	v_add_f32_dpp v138, v138, v138 quad_perm:[1,0,3,2] row_mask:0xf bank_mask:0xf
	v_add_f32_dpp v139, v139, v139 quad_perm:[1,0,3,2] row_mask:0xf bank_mask:0xf
	v_add_f32_dpp v140, v140, v140 quad_perm:[1,0,3,2] row_mask:0xf bank_mask:0xf
	v_add_f32_dpp v141, v141, v141 quad_perm:[1,0,3,2] row_mask:0xf bank_mask:0xf
	v_add_f32_dpp v142, v142, v142 quad_perm:[1,0,3,2] row_mask:0xf bank_mask:0xf
	v_add_f32_dpp v143, v143, v143 quad_perm:[1,0,3,2] row_mask:0xf bank_mask:0xf
	v_add_f32_dpp v144, v144, v144 quad_perm:[1,0,3,2] row_mask:0xf bank_mask:0xf
	v_add_f32_dpp v145, v145, v145 quad_perm:[1,0,3,2] row_mask:0xf bank_mask:0xf
	v_add_f32_dpp v138, v138, v138 quad_perm:[2,3,0,1] row_mask:0xf bank_mask:0xf
	v_add_f32_dpp v139, v139, v139 quad_perm:[2,3,0,1] row_mask:0xf bank_mask:0xf
	v_add_f32_dpp v140, v140, v140 quad_perm:[2,3,0,1] row_mask:0xf bank_mask:0xf
	v_add_f32_dpp v141, v141, v141 quad_perm:[2,3,0,1] row_mask:0xf bank_mask:0xf
	v_add_f32_dpp v142, v142, v142 quad_perm:[2,3,0,1] row_mask:0xf bank_mask:0xf
	v_add_f32_dpp v143, v143, v143 quad_perm:[2,3,0,1] row_mask:0xf bank_mask:0xf
	v_add_f32_dpp v144, v144, v144 quad_perm:[2,3,0,1] row_mask:0xf bank_mask:0xf
	v_add_f32_dpp v145, v145, v145 quad_perm:[2,3,0,1] row_mask:0xf bank_mask:0xf
	v_add_f32_dpp v138, v138, v138 row_half_mirror row_mask:0xf bank_mask:0xf
	v_add_f32_dpp v139, v139, v139 row_half_mirror row_mask:0xf bank_mask:0xf
	v_add_f32_dpp v140, v140, v140 row_half_mirror row_mask:0xf bank_mask:0xf
	v_add_f32_dpp v141, v141, v141 row_half_mirror row_mask:0xf bank_mask:0xf
	v_add_f32_dpp v142, v142, v142 row_half_mirror row_mask:0xf bank_mask:0xf
	v_add_f32_dpp v143, v143, v143 row_half_mirror row_mask:0xf bank_mask:0xf
	v_add_f32_dpp v144, v144, v144 row_half_mirror row_mask:0xf bank_mask:0xf
	v_add_f32_dpp v145, v145, v145 row_half_mirror row_mask:0xf bank_mask:0xf
	v_fmac_f32_e32 v146, v138, v148
	v_fmac_f32_e32 v146, v139, v149
	v_fmac_f32_e32 v146, v140, v150
	v_fmac_f32_e32 v146, v141, v151
	v_fmac_f32_e32 v146, v142, v152
	v_fmac_f32_e32 v146, v143, v153
	v_fmac_f32_e32 v146, v144, v154
	v_fmac_f32_e32 v146, v145, v155
	s_waitcnt lgkmcnt(0)
; DEV void phase_peer_expert(const Params& p, int layer, int M, bool final_, int part, char* smem) {
;     ...
; #pragma unroll 2
;     for (int st = 0; st < 16; st++) {
;       if (st + 1 < 16) {
;         const unsigned char* r0p = U + (size_t)se[(st + 1) * 8 + g] * 1024 + l16 * 16;
;         const unsigned char* r1p = U + (size_t)se[(st + 1) * 8 + 4 + g] * 1024 + l16 * 16;
; #pragma unroll
;         for (int c = 0; c < 4; c++) { nxt[c] = *(const u32x4*)(r0p + c * 256); nxt[4 + c] = *(const u32x4*)(r1p + c * 256); }
;       }
;       f32x2 da = (f32x2){0.f, 0.f}, db = (f32x2){0.f, 0.f};
; #pragma unroll
;       for (int c = 0; c < 4; c++) {
;         da = fp8dot4(cur[c][0], xf[c * 8 + 0], xf[c * 8 + 1], da); da = fp8dot4(cur[c][1], xf[c * 8 + 2], xf[c * 8 + 3], da);
;         da = fp8dot4(cur[c][2], xf[c * 8 + 4], xf[c * 8 + 5], da); da = fp8dot4(cur[c][3], xf[c * 8 + 6], xf[c * 8 + 7], da);
;         db = fp8dot4(cur[4 + c][0], xf[c * 8 + 0], xf[c * 8 + 1], db); db = fp8dot4(cur[4 + c][1], xf[c * 8 + 2], xf[c * 8 + 3], db);
;         db = fp8dot4(cur[4 + c][2], xf[c * 8 + 4], xf[c * 8 + 5], db); db = fp8dot4(cur[4 + c][3], xf[c * 8 + 6], xf[c * 8 + 7], db);
;       }
	v_add_u32_e32 v159, v66, v156
	global_load_dwordx4 v[2:5], v159, s[38:39]
	v_add_u32_e32 v159, v67, v156
	global_load_dwordx4 v[6:9], v159, s[38:39]
	v_add_u32_e32 v159, v68, v156
	global_load_dwordx4 v[10:13], v159, s[38:39]
	v_add_u32_e32 v159, v69, v156
	global_load_dwordx4 v[14:17], v159, s[38:39]
	v_add_u32_e32 v159, v70, v156
	global_load_dwordx4 v[18:21], v159, s[38:39]
	v_add_u32_e32 v159, v71, v156
	global_load_dwordx4 v[22:25], v159, s[38:39]
	v_add_u32_e32 v159, v72, v156
	global_load_dwordx4 v[26:29], v159, s[38:39]
	v_add_u32_e32 v159, v73, v156
	global_load_dwordx4 v[30:33], v159, s[38:39]
	s_waitcnt vmcnt(10)
	v_cvt_pk_f32_fp8_e32 v[122:123], v34
	v_cvt_pk_f32_fp8_e32 v[126:127], v38
	v_cvt_pk_f32_fp8_sdwa v[124:125], v34 src0_sel:WORD_1
	v_cvt_pk_f32_fp8_sdwa v[128:129], v38 src0_sel:WORD_1
	v_pk_fma_f32 v[106:107], v[122:123], v[90:91], 0 op_sel_hi:[1,1,0]
	v_pk_fma_f32 v[108:109], v[126:127], v[90:91], 0 op_sel_hi:[1,1,0]
	v_pk_fma_f32 v[106:107], v[124:125], v[92:93], v[106:107]
	v_pk_fma_f32 v[108:109], v[128:129], v[92:93], v[108:109]
	v_cvt_pk_f32_fp8_e32 v[122:123], v35
	v_cvt_pk_f32_fp8_e32 v[126:127], v39
	v_cvt_pk_f32_fp8_sdwa v[124:125], v35 src0_sel:WORD_1
	v_cvt_pk_f32_fp8_sdwa v[128:129], v39 src0_sel:WORD_1
	v_pk_fma_f32 v[106:107], v[122:123], v[94:95], v[106:107]
	v_pk_fma_f32 v[108:109], v[126:127], v[94:95], v[108:109]
	v_pk_fma_f32 v[106:107], v[124:125], v[96:97], v[106:107]
	v_pk_fma_f32 v[108:109], v[128:129], v[96:97], v[108:109]
	v_cvt_pk_f32_fp8_e32 v[122:123], v36
	v_cvt_pk_f32_fp8_e32 v[126:127], v40
	v_cvt_pk_f32_fp8_sdwa v[124:125], v36 src0_sel:WORD_1
	v_cvt_pk_f32_fp8_sdwa v[128:129], v40 src0_sel:WORD_1
	v_pk_fma_f32 v[106:107], v[122:123], v[98:99], v[106:107]
	v_pk_fma_f32 v[108:109], v[126:127], v[98:99], v[108:109]
	v_pk_fma_f32 v[106:107], v[124:125], v[100:101], v[106:107]
	v_pk_fma_f32 v[108:109], v[128:129], v[100:101], v[108:109]
	v_cvt_pk_f32_fp8_e32 v[122:123], v37
	v_cvt_pk_f32_fp8_e32 v[126:127], v41
	v_cvt_pk_f32_fp8_sdwa v[124:125], v37 src0_sel:WORD_1
	v_cvt_pk_f32_fp8_sdwa v[128:129], v41 src0_sel:WORD_1
	v_pk_fma_f32 v[106:107], v[122:123], v[102:103], v[106:107]
	v_pk_fma_f32 v[108:109], v[126:127], v[102:103], v[108:109]
	v_pk_fma_f32 v[106:107], v[124:125], v[104:105], v[106:107]
	v_pk_fma_f32 v[108:109], v[128:129], v[104:105], v[108:109]
	v_cvt_pk_f32_fp8_e32 v[122:123], v42
	v_cvt_pk_f32_fp8_e32 v[126:127], v46
	v_cvt_pk_f32_fp8_sdwa v[124:125], v42 src0_sel:WORD_1
	v_cvt_pk_f32_fp8_sdwa v[128:129], v46 src0_sel:WORD_1
	v_pk_fma_f32 v[110:111], v[122:123], v[90:91], 0 op_sel_hi:[1,1,0]
	v_pk_fma_f32 v[112:113], v[126:127], v[90:91], 0 op_sel_hi:[1,1,0]
	v_pk_fma_f32 v[110:111], v[124:125], v[92:93], v[110:111]
	v_pk_fma_f32 v[112:113], v[128:129], v[92:93], v[112:113]
	v_cvt_pk_f32_fp8_e32 v[122:123], v43
	v_cvt_pk_f32_fp8_e32 v[126:127], v47
	v_cvt_pk_f32_fp8_sdwa v[124:125], v43 src0_sel:WORD_1
	v_cvt_pk_f32_fp8_sdwa v[128:129], v47 src0_sel:WORD_1
	v_pk_fma_f32 v[110:111], v[122:123], v[94:95], v[110:111]
	v_pk_fma_f32 v[112:113], v[126:127], v[94:95], v[112:113]
	v_pk_fma_f32 v[110:111], v[124:125], v[96:97], v[110:111]
	v_pk_fma_f32 v[112:113], v[128:129], v[96:97], v[112:113]
	v_cvt_pk_f32_fp8_e32 v[122:123], v44
	v_cvt_pk_f32_fp8_e32 v[126:127], v48
	v_cvt_pk_f32_fp8_sdwa v[124:125], v44 src0_sel:WORD_1
	v_cvt_pk_f32_fp8_sdwa v[128:129], v48 src0_sel:WORD_1
	v_pk_fma_f32 v[110:111], v[122:123], v[98:99], v[110:111]
	v_pk_fma_f32 v[112:113], v[126:127], v[98:99], v[112:113]
	v_pk_fma_f32 v[110:111], v[124:125], v[100:101], v[110:111]
	v_pk_fma_f32 v[112:113], v[128:129], v[100:101], v[112:113]
	v_cvt_pk_f32_fp8_e32 v[122:123], v45
	v_cvt_pk_f32_fp8_e32 v[126:127], v49
	v_cvt_pk_f32_fp8_sdwa v[124:125], v45 src0_sel:WORD_1
	v_cvt_pk_f32_fp8_sdwa v[128:129], v49 src0_sel:WORD_1
	v_pk_fma_f32 v[110:111], v[122:123], v[102:103], v[110:111]
	v_pk_fma_f32 v[112:113], v[126:127], v[102:103], v[112:113]
	v_pk_fma_f32 v[110:111], v[124:125], v[104:105], v[110:111]
	v_pk_fma_f32 v[112:113], v[128:129], v[104:105], v[112:113]
	v_cvt_pk_f32_fp8_e32 v[122:123], v50
	v_cvt_pk_f32_fp8_e32 v[126:127], v54
	v_cvt_pk_f32_fp8_sdwa v[124:125], v50 src0_sel:WORD_1
	v_cvt_pk_f32_fp8_sdwa v[128:129], v54 src0_sel:WORD_1
	v_pk_fma_f32 v[114:115], v[122:123], v[90:91], 0 op_sel_hi:[1,1,0]
	v_pk_fma_f32 v[116:117], v[126:127], v[90:91], 0 op_sel_hi:[1,1,0]
	v_pk_fma_f32 v[114:115], v[124:125], v[92:93], v[114:115]
	v_pk_fma_f32 v[116:117], v[128:129], v[92:93], v[116:117]
	v_cvt_pk_f32_fp8_e32 v[122:123], v51
	v_cvt_pk_f32_fp8_e32 v[126:127], v55
	v_cvt_pk_f32_fp8_sdwa v[124:125], v51 src0_sel:WORD_1
	v_cvt_pk_f32_fp8_sdwa v[128:129], v55 src0_sel:WORD_1
	v_pk_fma_f32 v[114:115], v[122:123], v[94:95], v[114:115]
	v_pk_fma_f32 v[116:117], v[126:127], v[94:95], v[116:117]
	v_pk_fma_f32 v[114:115], v[124:125], v[96:97], v[114:115]
	v_pk_fma_f32 v[116:117], v[128:129], v[96:97], v[116:117]
	v_cvt_pk_f32_fp8_e32 v[122:123], v52
	v_cvt_pk_f32_fp8_e32 v[126:127], v56
	v_cvt_pk_f32_fp8_sdwa v[124:125], v52 src0_sel:WORD_1
	v_cvt_pk_f32_fp8_sdwa v[128:129], v56 src0_sel:WORD_1
	v_pk_fma_f32 v[114:115], v[122:123], v[98:99], v[114:115]
	v_pk_fma_f32 v[116:117], v[126:127], v[98:99], v[116:117]
	v_pk_fma_f32 v[114:115], v[124:125], v[100:101], v[114:115]
	v_pk_fma_f32 v[116:117], v[128:129], v[100:101], v[116:117]
	v_cvt_pk_f32_fp8_e32 v[122:123], v53
	v_cvt_pk_f32_fp8_e32 v[126:127], v57
	v_cvt_pk_f32_fp8_sdwa v[124:125], v53 src0_sel:WORD_1
	v_cvt_pk_f32_fp8_sdwa v[128:129], v57 src0_sel:WORD_1
	v_pk_fma_f32 v[114:115], v[122:123], v[102:103], v[114:115]
	v_pk_fma_f32 v[116:117], v[126:127], v[102:103], v[116:117]
; DEV void phase_peer_expert(const Params& p, int layer, int M, bool final_, int part, char* smem) {
;     ...
;       float d0 = da.x + da.y, d1 = db.x + db.y;
;       d0 += __shfl_xor(d0, 1); d1 += __shfl_xor(d1, 1);
;       d0 += __shfl_xor(d0, 2); d1 += __shfl_xor(d1, 2);
;       d0 += __shfl_xor(d0, 4); d1 += __shfl_xor(d1, 4);
;       d0 += __shfl_xor(d0, 8); d1 += __shfl_xor(d1, 8);
;       const int s0 = st * 8 + g, s1 = s0 + 4;
;       d0 *= su[s0]; d1 *= su[s1];
;       const float a0 = 0.5f * d0 * (1.f + erff(d0 * 0.70710678118f));
;       const float a1 = 0.5f * d1 * (1.f + erff(d1 * 0.70710678118f));
;       if (l16 == 0) { COEF[(size_t)m * 128 + s0] = sg[s0] * a0; COEF[(size_t)m * 128 + s1] = sg[s1] * a1; }
; #pragma unroll
;       for (int c = 0; c < 8; c++) cur[c] = nxt[c];
	v_pk_fma_f32 v[114:115], v[124:125], v[104:105], v[114:115]
	v_pk_fma_f32 v[116:117], v[128:129], v[104:105], v[116:117]
	v_cvt_pk_f32_fp8_e32 v[122:123], v58
	v_cvt_pk_f32_fp8_e32 v[126:127], v62
	v_cvt_pk_f32_fp8_sdwa v[124:125], v58 src0_sel:WORD_1
	v_cvt_pk_f32_fp8_sdwa v[128:129], v62 src0_sel:WORD_1
	v_pk_fma_f32 v[118:119], v[122:123], v[90:91], 0 op_sel_hi:[1,1,0]
	v_pk_fma_f32 v[120:121], v[126:127], v[90:91], 0 op_sel_hi:[1,1,0]
	v_pk_fma_f32 v[118:119], v[124:125], v[92:93], v[118:119]
	v_pk_fma_f32 v[120:121], v[128:129], v[92:93], v[120:121]
	v_cvt_pk_f32_fp8_e32 v[122:123], v59
	v_cvt_pk_f32_fp8_e32 v[126:127], v63
	v_cvt_pk_f32_fp8_sdwa v[124:125], v59 src0_sel:WORD_1
	v_cvt_pk_f32_fp8_sdwa v[128:129], v63 src0_sel:WORD_1
	v_pk_fma_f32 v[118:119], v[122:123], v[94:95], v[118:119]
	v_pk_fma_f32 v[120:121], v[126:127], v[94:95], v[120:121]
	v_pk_fma_f32 v[118:119], v[124:125], v[96:97], v[118:119]
	v_pk_fma_f32 v[120:121], v[128:129], v[96:97], v[120:121]
	v_cvt_pk_f32_fp8_e32 v[122:123], v60
	v_cvt_pk_f32_fp8_e32 v[126:127], v64
	v_cvt_pk_f32_fp8_sdwa v[124:125], v60 src0_sel:WORD_1
	v_cvt_pk_f32_fp8_sdwa v[128:129], v64 src0_sel:WORD_1
	v_pk_fma_f32 v[118:119], v[122:123], v[98:99], v[118:119]
	v_pk_fma_f32 v[120:121], v[126:127], v[98:99], v[120:121]
	v_pk_fma_f32 v[118:119], v[124:125], v[100:101], v[118:119]
	v_pk_fma_f32 v[120:121], v[128:129], v[100:101], v[120:121]
	v_cvt_pk_f32_fp8_e32 v[122:123], v61
	v_cvt_pk_f32_fp8_e32 v[126:127], v65
	v_cvt_pk_f32_fp8_sdwa v[124:125], v61 src0_sel:WORD_1
	v_cvt_pk_f32_fp8_sdwa v[128:129], v65 src0_sel:WORD_1
	v_pk_fma_f32 v[118:119], v[122:123], v[102:103], v[118:119]
	v_pk_fma_f32 v[120:121], v[126:127], v[102:103], v[120:121]
	v_pk_fma_f32 v[118:119], v[124:125], v[104:105], v[118:119]
	v_pk_fma_f32 v[120:121], v[128:129], v[104:105], v[120:121]
	s_nop 0
	v_add_f32_e32 v138, v106, v107
	v_add_f32_e32 v139, v108, v109
	v_add_f32_e32 v140, v110, v111
	v_add_f32_e32 v141, v112, v113
	v_add_f32_e32 v142, v114, v115
	v_add_f32_e32 v143, v116, v117
	v_add_f32_e32 v144, v118, v119
	v_add_f32_e32 v145, v120, v121
	s_nop 1
	v_add_f32_dpp v138, v138, v138 quad_perm:[1,0,3,2] row_mask:0xf bank_mask:0xf
	v_add_f32_dpp v139, v139, v139 quad_perm:[1,0,3,2] row_mask:0xf bank_mask:0xf
	v_add_f32_dpp v140, v140, v140 quad_perm:[1,0,3,2] row_mask:0xf bank_mask:0xf
	v_add_f32_dpp v141, v141, v141 quad_perm:[1,0,3,2] row_mask:0xf bank_mask:0xf
	v_add_f32_dpp v142, v142, v142 quad_perm:[1,0,3,2] row_mask:0xf bank_mask:0xf
	v_add_f32_dpp v143, v143, v143 quad_perm:[1,0,3,2] row_mask:0xf bank_mask:0xf
	v_add_f32_dpp v144, v144, v144 quad_perm:[1,0,3,2] row_mask:0xf bank_mask:0xf
	v_add_f32_dpp v145, v145, v145 quad_perm:[1,0,3,2] row_mask:0xf bank_mask:0xf
	v_add_f32_dpp v138, v138, v138 quad_perm:[2,3,0,1] row_mask:0xf bank_mask:0xf
	v_add_f32_dpp v139, v139, v139 quad_perm:[2,3,0,1] row_mask:0xf bank_mask:0xf
	v_add_f32_dpp v140, v140, v140 quad_perm:[2,3,0,1] row_mask:0xf bank_mask:0xf
	v_add_f32_dpp v141, v141, v141 quad_perm:[2,3,0,1] row_mask:0xf bank_mask:0xf
	v_add_f32_dpp v142, v142, v142 quad_perm:[2,3,0,1] row_mask:0xf bank_mask:0xf
	v_add_f32_dpp v143, v143, v143 quad_perm:[2,3,0,1] row_mask:0xf bank_mask:0xf
	v_add_f32_dpp v144, v144, v144 quad_perm:[2,3,0,1] row_mask:0xf bank_mask:0xf
	v_add_f32_dpp v145, v145, v145 quad_perm:[2,3,0,1] row_mask:0xf bank_mask:0xf
	v_add_f32_dpp v138, v138, v138 row_half_mirror row_mask:0xf bank_mask:0xf
	v_add_f32_dpp v139, v139, v139 row_half_mirror row_mask:0xf bank_mask:0xf
	v_add_f32_dpp v140, v140, v140 row_half_mirror row_mask:0xf bank_mask:0xf
	v_add_f32_dpp v141, v141, v141 row_half_mirror row_mask:0xf bank_mask:0xf
	v_add_f32_dpp v142, v142, v142 row_half_mirror row_mask:0xf bank_mask:0xf
	v_add_f32_dpp v143, v143, v143 row_half_mirror row_mask:0xf bank_mask:0xf
	v_add_f32_dpp v144, v144, v144 row_half_mirror row_mask:0xf bank_mask:0xf
	v_add_f32_dpp v145, v145, v145 row_half_mirror row_mask:0xf bank_mask:0xf
	v_fmac_f32_e32 v147, v138, v148
	v_fmac_f32_e32 v147, v139, v149
	v_fmac_f32_e32 v147, v140, v150
	v_fmac_f32_e32 v147, v141, v151
	v_fmac_f32_e32 v147, v142, v152
	v_fmac_f32_e32 v147, v143, v153
	v_fmac_f32_e32 v147, v144, v154
	v_fmac_f32_e32 v147, v145, v155
	v_add_u32_e32 v159, v74, v156
	global_load_dwordx4 v[34:37], v159, s[38:39]
	v_add_u32_e32 v159, v75, v156
	global_load_dwordx4 v[38:41], v159, s[38:39]
	v_add_u32_e32 v159, v76, v156
	global_load_dwordx4 v[42:45], v159, s[38:39]
	v_add_u32_e32 v159, v77, v156
	global_load_dwordx4 v[46:49], v159, s[38:39]
	v_add_u32_e32 v159, v78, v156
	global_load_dwordx4 v[50:53], v159, s[38:39]
	v_add_u32_e32 v159, v79, v156
	global_load_dwordx4 v[54:57], v159, s[38:39]
	v_add_u32_e32 v159, v80, v156
	global_load_dwordx4 v[58:61], v159, s[38:39]
	v_add_u32_e32 v159, v81, v156
	global_load_dwordx4 v[62:65], v159, s[38:39]
	s_lshl_b32 s40, s18, 9
	v_add_u32_e32 v160, s40, v161
	ds_add_f32 v160, v146
	ds_add_f32 v160, v147 offset:256
	s_waitcnt vmcnt(16)
	v_lshlrev_b32_e32 v90, 16, v82
	v_and_b32_e32 v91, 0xffff0000, v82
	v_lshlrev_b32_e32 v92, 16, v83
	v_and_b32_e32 v93, 0xffff0000, v83
	v_lshlrev_b32_e32 v94, 16, v84
	v_and_b32_e32 v95, 0xffff0000, v84
	v_lshlrev_b32_e32 v96, 16, v85
	v_and_b32_e32 v97, 0xffff0000, v85
	v_lshlrev_b32_e32 v98, 16, v86
	v_and_b32_e32 v99, 0xffff0000, v86
	v_lshlrev_b32_e32 v100, 16, v87
	v_and_b32_e32 v101, 0xffff0000, v87
	v_lshlrev_b32_e32 v102, 16, v88
	v_and_b32_e32 v103, 0xffff0000, v88
	v_lshlrev_b32_e32 v104, 16, v89
	v_and_b32_e32 v105, 0xffff0000, v89
	s_mov_b32 s18, s22
	s_mov_b32 s20, s28
	s_add_u32 s22, s22, 1
	s_cmp_lt_u32 s22, s8
	s_cbranch_scc1 .Lu_nx_ok
	s_mov_b32 s22, 0
	s_add_u32 s28, s28, 1
	s_cmp_lt_u32 s28, 8
	s_cbranch_scc1 .Lu_nx_ok
	s_mov_b32 s22, s18
	s_mov_b32 s28, s20
; DEV void phase_peer_expert(const Params& p, int layer, int M, bool final_, int part, char* smem) {
;     ...
;       const int s0 = st * 8 + g, s1 = s0 + 4;
;       d0 *= su[s0]; d1 *= su[s1];
;       const float a0 = 0.5f * d0 * (1.f + erff(d0 * 0.70710678118f));
;       const float a1 = 0.5f * d1 * (1.f + erff(d1 * 0.70710678118f));
;       if (l16 == 0) { COEF[(size_t)m * 128 + s0] = sg[s0] * a0; COEF[(size_t)m * 128 + s1] = sg[s1] * a1; }
;     ...
;   for (int m = blockIdx.x * 4 + w; m < M; m += gridDim.x * 4) {
;     {
;       int2 e2 = *(const int2*)(EIDX + (size_t)m * 128 + lane * 2);
;       float2 c2 = *(const float2*)(COEF + (size_t)m * 128 + lane * 2);
;       *(int2*)(se + lane * 2) = e2; *(float2*)(coefs + lane * 2) = c2;
;     }
.Lu_nx_ok:
	s_mul_i32 s29, s22, 0x2200
	s_lshl_b32 s40, s28, 8
	s_add_u32 s29, s29, s40
	s_lshl_b32 s40, s28, 21
	s_add_u32 s38, s14, s40
	s_addc_u32 s39, s15, 0
	s_lshl_b32 s32, s22, 9
	s_sub_u32 s37, s37, 1
	s_cmp_lg_u32 s37, 0
	s_cbranch_scc1 .Lu_loop
	s_waitcnt vmcnt(0) lgkmcnt(0)
	s_mov_b32 s18, 0
.Lu_tail:
	s_lshl_b32 s40, s18, 2
	s_add_u32 s40, s40, s9
	s_lshl_b32 s40, s40, 9
	v_add_u32_e32 v159, s40, v165
	global_load_dword v2, v159, s[16:17] offset:0
	global_load_dword v3, v159, s[16:17] offset:256
	v_add_u32_e32 v173, 0x840000, v159
	global_load_dword v4, v173, s[16:17] offset:0
	global_load_dword v5, v173, s[16:17] offset:256
	s_lshl_b32 s41, s18, 9
	v_add_u32_e32 v160, s41, v161
	ds_read_b32 v6, v160
	ds_read_b32 v7, v160 offset:256
	s_waitcnt vmcnt(0) lgkmcnt(0)
	v_mul_f32_e32 v6, v6, v4
	v_mul_f32_e32 v7, v7, v5
	v_mul_f32_e32 v10, 0x3f3504f3, v6
	v_fma_f32 v11, |v10|, s33, v222
	v_fma_f32 v11, |v10|, v11, s26
	v_fma_f32 v11, |v10|, v11, s27
	v_fma_f32 v11, |v10|, v11, s4
	v_fma_f32 v11, |v10|, v11, s5
	v_fma_f32 v11, |v10|, v11, s96
	v_fma_f32 v11, |v10|, v11, |v10|
	v_mul_f32_e32 v12, 0xbfb8aa3b, v11
	v_fma_f32 v13, v11, s97, -v12
	v_rndne_f32_e32 v14, v12
	v_fmac_f32_e32 v13, 0xb2a5705f, v11
	v_sub_f32_e32 v12, v12, v14
	v_add_f32_e32 v12, v12, v13
	v_cvt_i32_f32_e32 v13, v14
	v_exp_f32_e32 v12, v12
	v_cmp_nlt_f32_e32 vcc, s24, v11
	v_ldexp_f32 v12, v12, v13
	s_nop 0
	v_cndmask_b32_e32 v12, 0, v12, vcc
	v_cmp_ngt_f32_e32 vcc, s25, v11
	s_nop 1
	v_cndmask_b32_e32 v11, v223, v12, vcc
	v_sub_f32_e32 v11, 1.0, v11
	v_mul_f32_e32 v14, v10, v10
	v_fmamk_f32 v15, v14, 0xba1345e1, v196
	v_fmaak_f32 v15, v14, v15, 0xbcdac9b8
	v_fmaak_f32 v15, v14, v15, 0x3de703be
	v_fmaak_f32 v15, v14, v15, 0xbec09330
	v_fmaak_f32 v15, v14, v15, 0x3e0375d0
	v_fma_f32 v15, |v10|, v15, |v10|
	v_cmp_nlt_f32_e64 vcc, |v10|, 1.0
	s_nop 1
	v_cndmask_b32_e32 v11, v15, v11, vcc
	v_bfi_b32 v11, s50, v11, v10
	v_add_f32_e32 v11, 1.0, v11
	v_mul_f32_e32 v12, 0.5, v6
	v_mul_f32_e32 v11, v12, v11
	v_mul_f32_e32 v8, v11, v2
	v_mul_f32_e32 v10, 0x3f3504f3, v7
	v_fma_f32 v11, |v10|, s33, v222
	v_fma_f32 v11, |v10|, v11, s26
	v_fma_f32 v11, |v10|, v11, s27
	v_fma_f32 v11, |v10|, v11, s4
	v_fma_f32 v11, |v10|, v11, s5
	v_fma_f32 v11, |v10|, v11, s96
	v_fma_f32 v11, |v10|, v11, |v10|
	v_mul_f32_e32 v12, 0xbfb8aa3b, v11
	v_fma_f32 v13, v11, s97, -v12
	v_rndne_f32_e32 v14, v12
	v_fmac_f32_e32 v13, 0xb2a5705f, v11
	v_sub_f32_e32 v12, v12, v14
	v_add_f32_e32 v12, v12, v13
	v_cvt_i32_f32_e32 v13, v14
	v_exp_f32_e32 v12, v12
	v_cmp_nlt_f32_e32 vcc, s24, v11
	v_ldexp_f32 v12, v12, v13
	s_nop 0
	v_cndmask_b32_e32 v12, 0, v12, vcc
	v_cmp_ngt_f32_e32 vcc, s25, v11
	s_nop 1
	v_cndmask_b32_e32 v11, v223, v12, vcc
	v_sub_f32_e32 v11, 1.0, v11
	v_mul_f32_e32 v14, v10, v10
	v_fmamk_f32 v15, v14, 0xba1345e1, v196
	v_fmaak_f32 v15, v14, v15, 0xbcdac9b8
	v_fmaak_f32 v15, v14, v15, 0x3de703be
	v_fmaak_f32 v15, v14, v15, 0xbec09330
	v_fmaak_f32 v15, v14, v15, 0x3e0375d0
	v_fma_f32 v15, |v10|, v15, |v10|
	v_cmp_nlt_f32_e64 vcc, |v10|, 1.0
	s_nop 1
	v_cndmask_b32_e32 v11, v15, v11, vcc
	v_bfi_b32 v11, s50, v11, v10
	v_add_f32_e32 v11, 1.0, v11
	v_mul_f32_e32 v12, 0.5, v7
	v_mul_f32_e32 v11, v12, v11
	v_mul_f32_e32 v9, v11, v3
	global_store_dword v159, v8, s[2:3]
	global_store_dword v159, v9, s[2:3] offset:256
	s_add_u32 s18, s18, 1
	s_cmp_lt_u32 s18, s8
	s_cbranch_scc1 .Lu_tail
	s_branch .Lpeer_grid_barrier
.Lpeer_v:
	s_add_u32 s14, s0, s45
	s_addc_u32 s15, s1, 0
	s_add_u32 s16, s0, s52
	s_addc_u32 s17, s1, 0
	s_add_u32 s12, s0, s43
	s_addc_u32 s13, s1, 0
	v_add_u32_e32 v177, 0x4800, v167
	v_add_u32_e32 v159, 0, v166
	global_load_dwordx2 v[2:3], v159, s[12:13]
	v_add_u32_e32 v159, 2048, v166
	global_load_dwordx2 v[4:5], v159, s[12:13]
	v_add_u32_e32 v159, 4096, v166
	global_load_dwordx2 v[6:7], v159, s[12:13]
	v_add_u32_e32 v159, 6144, v166
	global_load_dwordx2 v[8:9], v159, s[12:13]
	v_add_u32_e32 v159, 8192, v166
	global_load_dwordx2 v[10:11], v159, s[12:13]
	v_add_u32_e32 v159, 10240, v166
	global_load_dwordx2 v[12:13], v159, s[12:13]
	v_add_u32_e32 v159, 12288, v166
	global_load_dwordx2 v[14:15], v159, s[12:13]
	v_add_u32_e32 v159, 14336, v166
	global_load_dwordx2 v[16:17], v159, s[12:13]
	v_add_u32_e32 v159, 16384, v166
	global_load_dwordx2 v[18:19], v159, s[12:13]
	s_waitcnt vmcnt(0)
	ds_write_b32 v177, v2 offset:0
	ds_write_b32 v177, v3 offset:64
	ds_write_b32 v177, v4 offset:512
	ds_write_b32 v177, v5 offset:576
	ds_write_b32 v177, v6 offset:1024
	ds_write_b32 v177, v7 offset:1088
	ds_write_b32 v177, v8 offset:1536
	ds_write_b32 v177, v9 offset:1600
	ds_write_b32 v177, v10 offset:2048
	ds_write_b32 v177, v11 offset:2112
	ds_write_b32 v177, v12 offset:2560
	ds_write_b32 v177, v13 offset:2624
	ds_write_b32 v177, v14 offset:3072
	ds_write_b32 v177, v15 offset:3136
	ds_write_b32 v177, v16 offset:3584
	ds_write_b32 v177, v17 offset:3648
	ds_write_b32 v177, v18 offset:4096
	ds_write_b32 v177, v19 offset:4160
	v_add_u32_e32 v172, 0x4800, v157
	s_lshl_b32 s40, s6, 12
	s_add_u32 s40, s40, 0x9000
	v_lshl_add_u32 v169, v164, 9, s40
	v_add_u32_e32 v169, v169, v156
	v_lshl_add_u32 v170, v162, 3, s40
	s_mul_i32 s40, s6, 0x900
	s_add_u32 s40, s40, 0xd000
	v_lshl_add_u32 v171, v162, 2, s40
	v_bfe_u32 v159, v162, 1, 3
	v_lshlrev_b32_e32 v159, 4, v159
	v_lshrrev_b32_e32 v160, 4, v162
	v_lshl_add_u32 v159, v160, 2, v159
	v_and_b32_e32 v160, 1, v162
	v_lshl_add_u32 v159, v160, 1, v159
	v_lshlrev_b32_e32 v168, 2, v159
	v_xor_b32_e32 v175, 16, v162
	v_lshlrev_b32_e32 v175, 2, v175
	v_xor_b32_e32 v176, 32, v162
	v_lshlrev_b32_e32 v176, 2, v176
	v_mov_b32_e32 v160, 0
	ds_write_b32 v171, v160 offset:0
	ds_write_b32 v171, v160 offset:256
	ds_write_b32 v171, v160 offset:512
	ds_write_b32 v171, v160 offset:768
	ds_write_b32 v171, v160 offset:1024
	ds_write_b32 v171, v160 offset:1280
	ds_write_b32 v171, v160 offset:1536
	ds_write_b32 v171, v160 offset:1792
	ds_write_b32 v171, v160 offset:2048
	s_waitcnt lgkmcnt(0)
; DEV void phase_peer_expert(const Params& p, int layer, int M, bool final_, int part, char* smem) {
;     ...
;     {
;       const unsigned char* r0p = V + (size_t)se[g] * 1024 + l16 * 16;
;       const unsigned char* r1p = V + (size_t)se[4 + g] * 1024 + l16 * 16;
; #pragma unroll
;       for (int c = 0; c < 4; c++) { cur[c] = *(const u32x4*)(r0p + c * 256); cur[4 + c] = *(const u32x4*)(r1p + c * 256); }
;     }
; #pragma unroll 2
;     for (int st = 0; st < 16; st++) {
;       if (st + 1 < 16) {
;         const unsigned char* r0p = V + (size_t)se[(st + 1) * 8 + g] * 1024 + l16 * 16;
;         const unsigned char* r1p = V + (size_t)se[(st + 1) * 8 + 4 + g] * 1024 + l16 * 16;
; #pragma unroll
;         for (int c = 0; c < 4; c++) { nxt[c] = *(const u32x4*)(r0p + c * 256); nxt[4 + c] = *(const u32x4*)(r1p + c * 256); }
;     ...
;       const float c0 = coefs[st * 8 + g], c1 = coefs[st * 8 + 4 + g];
;       const f32x2 ca = (f32x2){c0, c0}, cb = (f32x2){c1, c1};
; #pragma unroll
;       for (int c = 0; c < 4; c++) {
; #pragma unroll
;         for (int d = 0; d < 4; d++) {
;           acc[c * 8 + d * 2 + 0] += ca * __builtin_amdgcn_cvt_pk_f32_fp8((int)cur[c][d], false);
;           acc[c * 8 + d * 2 + 1] += ca * __builtin_amdgcn_cvt_pk_f32_fp8((int)cur[c][d], true);
;           acc[c * 8 + d * 2 + 0] += cb * __builtin_amdgcn_cvt_pk_f32_fp8((int)cur[4 + c][d], false);
;           acc[c * 8 + d * 2 + 1] += cb * __builtin_amdgcn_cvt_pk_f32_fp8((int)cur[4 + c][d], true);
;         }
;       }
	s_mov_b32 s18, 0
	s_mov_b32 s20, 0
	ds_read_b128 v[66:69], v157 offset:0
	ds_read_b128 v[70:73], v157 offset:16
	ds_read_b128 v[74:77], v157 offset:32
	ds_read_b128 v[78:81], v157 offset:48
	s_waitcnt lgkmcnt(0)
	v_add_u32_e32 v159, v66, v156
	global_load_dwordx4 v[2:5], v159, s[14:15]
	v_add_u32_e32 v159, v67, v156
	global_load_dwordx4 v[6:9], v159, s[14:15]
	v_add_u32_e32 v159, v68, v156
	global_load_dwordx4 v[10:13], v159, s[14:15]
	v_add_u32_e32 v159, v69, v156
	global_load_dwordx4 v[14:17], v159, s[14:15]
	v_add_u32_e32 v159, v70, v156
	global_load_dwordx4 v[18:21], v159, s[14:15]
	v_add_u32_e32 v159, v71, v156
	global_load_dwordx4 v[22:25], v159, s[14:15]
	v_add_u32_e32 v159, v72, v156
	global_load_dwordx4 v[26:29], v159, s[14:15]
	v_add_u32_e32 v159, v73, v156
	global_load_dwordx4 v[30:33], v159, s[14:15]
	v_add_u32_e32 v159, v74, v156
	global_load_dwordx4 v[34:37], v159, s[14:15]
	v_add_u32_e32 v159, v75, v156
	global_load_dwordx4 v[38:41], v159, s[14:15]
	v_add_u32_e32 v159, v76, v156
	global_load_dwordx4 v[42:45], v159, s[14:15]
	v_add_u32_e32 v159, v77, v156
	global_load_dwordx4 v[46:49], v159, s[14:15]
	v_add_u32_e32 v159, v78, v156
	global_load_dwordx4 v[50:53], v159, s[14:15]
	v_add_u32_e32 v159, v79, v156
	global_load_dwordx4 v[54:57], v159, s[14:15]
	v_add_u32_e32 v159, v80, v156
	global_load_dwordx4 v[58:61], v159, s[14:15]
	v_add_u32_e32 v159, v81, v156
	global_load_dwordx4 v[62:65], v159, s[14:15]
	global_load_dword v178, v168, s[0:1]
	s_lshl_b32 s40, s18, 2
	s_add_u32 s40, s40, s9
	s_lshr_b32 s42, s40, 13
	s_min_u32 s42, s42, 2
	s_mul_i32 s42, s42, 0x6000
	s_lshl_b32 s41, s40, 12
	s_lshl_b32 s43, s20, 9
	s_add_u32 s41, s41, s43
	s_add_u32 s42, s42, s43
	v_add_u32_e32 v173, s41, v168
	global_load_dwordx2 v[122:123], v173, s[0:1]
	v_add_u32_e32 v174, s42, v168
	global_load_dwordx2 v[124:125], v174, s[16:17]
	s_mov_b32 s22, 1
	s_mov_b32 s28, 0
	s_lshl_b32 s40, s28, 21
	s_add_u32 s38, s14, s40
	s_addc_u32 s39, s15, 0
	s_lshl_b32 s32, s22, 9
	ds_read_b128 v[82:85], v172 offset:0
	ds_read_b128 v[86:89], v172 offset:16
	ds_read_b128 v[90:93], v172 offset:32
	ds_read_b128 v[94:97], v172 offset:48
	v_add_u32_e32 v160, s32, v157
	ds_read_b128 v[66:69], v160 offset:0
	ds_read_b128 v[70:73], v160 offset:16
	ds_read_b128 v[74:77], v160 offset:32
	ds_read_b128 v[78:81], v160 offset:48
	s_lshl_b32 s37, s8, 3
.Lv_loop:
	s_waitcnt vmcnt(11) lgkmcnt(0)
	v_cvt_pk_f32_fp8_e32 v[114:115], v2
	v_cvt_pk_f32_fp8_sdwa v[116:117], v2 src0_sel:WORD_1
	v_pk_fma_f32 v[98:99], v[82:83], v[114:115], 0 op_sel_hi:[0,1,0]
	v_pk_fma_f32 v[100:101], v[82:83], v[116:117], 0 op_sel_hi:[0,1,0]
	v_cvt_pk_f32_fp8_e32 v[118:119], v3
	v_cvt_pk_f32_fp8_sdwa v[120:121], v3 src0_sel:WORD_1
	v_pk_fma_f32 v[102:103], v[82:83], v[118:119], 0 op_sel_hi:[0,1,0]
	v_pk_fma_f32 v[104:105], v[82:83], v[120:121], 0 op_sel_hi:[0,1,0]
	v_cvt_pk_f32_fp8_e32 v[114:115], v4
	v_cvt_pk_f32_fp8_sdwa v[116:117], v4 src0_sel:WORD_1
	v_pk_fma_f32 v[106:107], v[82:83], v[114:115], 0 op_sel_hi:[0,1,0]
	v_pk_fma_f32 v[108:109], v[82:83], v[116:117], 0 op_sel_hi:[0,1,0]
	v_cvt_pk_f32_fp8_e32 v[118:119], v5
	v_cvt_pk_f32_fp8_sdwa v[120:121], v5 src0_sel:WORD_1
	v_pk_fma_f32 v[110:111], v[82:83], v[118:119], 0 op_sel_hi:[0,1,0]
	v_pk_fma_f32 v[112:113], v[82:83], v[120:121], 0 op_sel_hi:[0,1,0]
	v_cvt_pk_f32_fp8_e32 v[114:115], v6
	v_cvt_pk_f32_fp8_sdwa v[116:117], v6 src0_sel:WORD_1
	v_pk_fma_f32 v[98:99], v[82:83], v[114:115], v[98:99] op_sel:[1,0,0] op_sel_hi:[1,1,1]
	v_pk_fma_f32 v[100:101], v[82:83], v[116:117], v[100:101] op_sel:[1,0,0] op_sel_hi:[1,1,1]
	v_cvt_pk_f32_fp8_e32 v[118:119], v7
	v_cvt_pk_f32_fp8_sdwa v[120:121], v7 src0_sel:WORD_1
	v_pk_fma_f32 v[102:103], v[82:83], v[118:119], v[102:103] op_sel:[1,0,0] op_sel_hi:[1,1,1]
	v_pk_fma_f32 v[104:105], v[82:83], v[120:121], v[104:105] op_sel:[1,0,0] op_sel_hi:[1,1,1]
	v_cvt_pk_f32_fp8_e32 v[114:115], v8
	v_cvt_pk_f32_fp8_sdwa v[116:117], v8 src0_sel:WORD_1
	v_pk_fma_f32 v[106:107], v[82:83], v[114:115], v[106:107] op_sel:[1,0,0] op_sel_hi:[1,1,1]
	v_pk_fma_f32 v[108:109], v[82:83], v[116:117], v[108:109] op_sel:[1,0,0] op_sel_hi:[1,1,1]
	v_cvt_pk_f32_fp8_e32 v[118:119], v9
	v_cvt_pk_f32_fp8_sdwa v[120:121], v9 src0_sel:WORD_1
	v_pk_fma_f32 v[110:111], v[82:83], v[118:119], v[110:111] op_sel:[1,0,0] op_sel_hi:[1,1,1]
	v_pk_fma_f32 v[112:113], v[82:83], v[120:121], v[112:113] op_sel:[1,0,0] op_sel_hi:[1,1,1]
	v_cvt_pk_f32_fp8_e32 v[114:115], v10
	v_cvt_pk_f32_fp8_sdwa v[116:117], v10 src0_sel:WORD_1
	v_pk_fma_f32 v[98:99], v[84:85], v[114:115], v[98:99] op_sel_hi:[0,1,1]
	v_pk_fma_f32 v[100:101], v[84:85], v[116:117], v[100:101] op_sel_hi:[0,1,1]
	v_cvt_pk_f32_fp8_e32 v[118:119], v11
	v_cvt_pk_f32_fp8_sdwa v[120:121], v11 src0_sel:WORD_1
	v_pk_fma_f32 v[102:103], v[84:85], v[118:119], v[102:103] op_sel_hi:[0,1,1]
	v_pk_fma_f32 v[104:105], v[84:85], v[120:121], v[104:105] op_sel_hi:[0,1,1]
	v_cvt_pk_f32_fp8_e32 v[114:115], v12
	v_cvt_pk_f32_fp8_sdwa v[116:117], v12 src0_sel:WORD_1
	v_pk_fma_f32 v[106:107], v[84:85], v[114:115], v[106:107] op_sel_hi:[0,1,1]
	v_pk_fma_f32 v[108:109], v[84:85], v[116:117], v[108:109] op_sel_hi:[0,1,1]
	v_cvt_pk_f32_fp8_e32 v[118:119], v13
	v_cvt_pk_f32_fp8_sdwa v[120:121], v13 src0_sel:WORD_1
	v_pk_fma_f32 v[110:111], v[84:85], v[118:119], v[110:111] op_sel_hi:[0,1,1]
	v_pk_fma_f32 v[112:113], v[84:85], v[120:121], v[112:113] op_sel_hi:[0,1,1]
	v_cvt_pk_f32_fp8_e32 v[114:115], v14
	v_cvt_pk_f32_fp8_sdwa v[116:117], v14 src0_sel:WORD_1
	v_pk_fma_f32 v[98:99], v[84:85], v[114:115], v[98:99] op_sel:[1,0,0] op_sel_hi:[1,1,1]
	v_pk_fma_f32 v[100:101], v[84:85], v[116:117], v[100:101] op_sel:[1,0,0] op_sel_hi:[1,1,1]
; DEV void phase_peer_expert(const Params& p, int layer, int M, bool final_, int part, char* smem) {
;     ...
;       const float c0 = coefs[st * 8 + g], c1 = coefs[st * 8 + 4 + g];
;       const f32x2 ca = (f32x2){c0, c0}, cb = (f32x2){c1, c1};
; #pragma unroll
;       for (int c = 0; c < 4; c++) {
; #pragma unroll
;         for (int d = 0; d < 4; d++) {
;           acc[c * 8 + d * 2 + 0] += ca * __builtin_amdgcn_cvt_pk_f32_fp8((int)cur[c][d], false);
;           acc[c * 8 + d * 2 + 1] += ca * __builtin_amdgcn_cvt_pk_f32_fp8((int)cur[c][d], true);
;           acc[c * 8 + d * 2 + 0] += cb * __builtin_amdgcn_cvt_pk_f32_fp8((int)cur[4 + c][d], false);
;           acc[c * 8 + d * 2 + 1] += cb * __builtin_amdgcn_cvt_pk_f32_fp8((int)cur[4 + c][d], true);
;         }
;       }
	v_cvt_pk_f32_fp8_e32 v[118:119], v15
	v_cvt_pk_f32_fp8_sdwa v[120:121], v15 src0_sel:WORD_1
	v_pk_fma_f32 v[102:103], v[84:85], v[118:119], v[102:103] op_sel:[1,0,0] op_sel_hi:[1,1,1]
	v_pk_fma_f32 v[104:105], v[84:85], v[120:121], v[104:105] op_sel:[1,0,0] op_sel_hi:[1,1,1]
	v_cvt_pk_f32_fp8_e32 v[114:115], v16
	v_cvt_pk_f32_fp8_sdwa v[116:117], v16 src0_sel:WORD_1
	v_pk_fma_f32 v[106:107], v[84:85], v[114:115], v[106:107] op_sel:[1,0,0] op_sel_hi:[1,1,1]
	v_pk_fma_f32 v[108:109], v[84:85], v[116:117], v[108:109] op_sel:[1,0,0] op_sel_hi:[1,1,1]
	v_cvt_pk_f32_fp8_e32 v[118:119], v17
	v_cvt_pk_f32_fp8_sdwa v[120:121], v17 src0_sel:WORD_1
	v_pk_fma_f32 v[110:111], v[84:85], v[118:119], v[110:111] op_sel:[1,0,0] op_sel_hi:[1,1,1]
	v_pk_fma_f32 v[112:113], v[84:85], v[120:121], v[112:113] op_sel:[1,0,0] op_sel_hi:[1,1,1]
	v_cvt_pk_f32_fp8_e32 v[114:115], v18
	v_cvt_pk_f32_fp8_sdwa v[116:117], v18 src0_sel:WORD_1
	v_pk_fma_f32 v[98:99], v[86:87], v[114:115], v[98:99] op_sel_hi:[0,1,1]
	v_pk_fma_f32 v[100:101], v[86:87], v[116:117], v[100:101] op_sel_hi:[0,1,1]
	v_cvt_pk_f32_fp8_e32 v[118:119], v19
	v_cvt_pk_f32_fp8_sdwa v[120:121], v19 src0_sel:WORD_1
	v_pk_fma_f32 v[102:103], v[86:87], v[118:119], v[102:103] op_sel_hi:[0,1,1]
	v_pk_fma_f32 v[104:105], v[86:87], v[120:121], v[104:105] op_sel_hi:[0,1,1]
	v_cvt_pk_f32_fp8_e32 v[114:115], v20
	v_cvt_pk_f32_fp8_sdwa v[116:117], v20 src0_sel:WORD_1
	v_pk_fma_f32 v[106:107], v[86:87], v[114:115], v[106:107] op_sel_hi:[0,1,1]
	v_pk_fma_f32 v[108:109], v[86:87], v[116:117], v[108:109] op_sel_hi:[0,1,1]
	v_cvt_pk_f32_fp8_e32 v[118:119], v21
	v_cvt_pk_f32_fp8_sdwa v[120:121], v21 src0_sel:WORD_1
	v_pk_fma_f32 v[110:111], v[86:87], v[118:119], v[110:111] op_sel_hi:[0,1,1]
	v_pk_fma_f32 v[112:113], v[86:87], v[120:121], v[112:113] op_sel_hi:[0,1,1]
	v_cvt_pk_f32_fp8_e32 v[114:115], v22
	v_cvt_pk_f32_fp8_sdwa v[116:117], v22 src0_sel:WORD_1
	v_pk_fma_f32 v[98:99], v[86:87], v[114:115], v[98:99] op_sel:[1,0,0] op_sel_hi:[1,1,1]
	v_pk_fma_f32 v[100:101], v[86:87], v[116:117], v[100:101] op_sel:[1,0,0] op_sel_hi:[1,1,1]
	v_cvt_pk_f32_fp8_e32 v[118:119], v23
	v_cvt_pk_f32_fp8_sdwa v[120:121], v23 src0_sel:WORD_1
	v_pk_fma_f32 v[102:103], v[86:87], v[118:119], v[102:103] op_sel:[1,0,0] op_sel_hi:[1,1,1]
	v_pk_fma_f32 v[104:105], v[86:87], v[120:121], v[104:105] op_sel:[1,0,0] op_sel_hi:[1,1,1]
	v_cvt_pk_f32_fp8_e32 v[114:115], v24
	v_cvt_pk_f32_fp8_sdwa v[116:117], v24 src0_sel:WORD_1
	v_pk_fma_f32 v[106:107], v[86:87], v[114:115], v[106:107] op_sel:[1,0,0] op_sel_hi:[1,1,1]
	v_pk_fma_f32 v[108:109], v[86:87], v[116:117], v[108:109] op_sel:[1,0,0] op_sel_hi:[1,1,1]
	v_cvt_pk_f32_fp8_e32 v[118:119], v25
	v_cvt_pk_f32_fp8_sdwa v[120:121], v25 src0_sel:WORD_1
	v_pk_fma_f32 v[110:111], v[86:87], v[118:119], v[110:111] op_sel:[1,0,0] op_sel_hi:[1,1,1]
	v_pk_fma_f32 v[112:113], v[86:87], v[120:121], v[112:113] op_sel:[1,0,0] op_sel_hi:[1,1,1]
	v_cvt_pk_f32_fp8_e32 v[114:115], v26
	v_cvt_pk_f32_fp8_sdwa v[116:117], v26 src0_sel:WORD_1
	v_pk_fma_f32 v[98:99], v[88:89], v[114:115], v[98:99] op_sel_hi:[0,1,1]
	v_pk_fma_f32 v[100:101], v[88:89], v[116:117], v[100:101] op_sel_hi:[0,1,1]
	v_cvt_pk_f32_fp8_e32 v[118:119], v27
	v_cvt_pk_f32_fp8_sdwa v[120:121], v27 src0_sel:WORD_1
	v_pk_fma_f32 v[102:103], v[88:89], v[118:119], v[102:103] op_sel_hi:[0,1,1]
	v_pk_fma_f32 v[104:105], v[88:89], v[120:121], v[104:105] op_sel_hi:[0,1,1]
	v_cvt_pk_f32_fp8_e32 v[114:115], v28
	v_cvt_pk_f32_fp8_sdwa v[116:117], v28 src0_sel:WORD_1
	v_pk_fma_f32 v[106:107], v[88:89], v[114:115], v[106:107] op_sel_hi:[0,1,1]
	v_pk_fma_f32 v[108:109], v[88:89], v[116:117], v[108:109] op_sel_hi:[0,1,1]
	v_cvt_pk_f32_fp8_e32 v[118:119], v29
	v_cvt_pk_f32_fp8_sdwa v[120:121], v29 src0_sel:WORD_1
	v_pk_fma_f32 v[110:111], v[88:89], v[118:119], v[110:111] op_sel_hi:[0,1,1]
	v_pk_fma_f32 v[112:113], v[88:89], v[120:121], v[112:113] op_sel_hi:[0,1,1]
	v_cvt_pk_f32_fp8_e32 v[114:115], v30
	v_cvt_pk_f32_fp8_sdwa v[116:117], v30 src0_sel:WORD_1
	v_pk_fma_f32 v[98:99], v[88:89], v[114:115], v[98:99] op_sel:[1,0,0] op_sel_hi:[1,1,1]
	v_pk_fma_f32 v[100:101], v[88:89], v[116:117], v[100:101] op_sel:[1,0,0] op_sel_hi:[1,1,1]
	v_cvt_pk_f32_fp8_e32 v[118:119], v31
	v_cvt_pk_f32_fp8_sdwa v[120:121], v31 src0_sel:WORD_1
	v_pk_fma_f32 v[102:103], v[88:89], v[118:119], v[102:103] op_sel:[1,0,0] op_sel_hi:[1,1,1]
	v_pk_fma_f32 v[104:105], v[88:89], v[120:121], v[104:105] op_sel:[1,0,0] op_sel_hi:[1,1,1]
	v_cvt_pk_f32_fp8_e32 v[114:115], v32
	v_cvt_pk_f32_fp8_sdwa v[116:117], v32 src0_sel:WORD_1
	v_pk_fma_f32 v[106:107], v[88:89], v[114:115], v[106:107] op_sel:[1,0,0] op_sel_hi:[1,1,1]
	v_pk_fma_f32 v[108:109], v[88:89], v[116:117], v[108:109] op_sel:[1,0,0] op_sel_hi:[1,1,1]
	v_cvt_pk_f32_fp8_e32 v[118:119], v33
	v_cvt_pk_f32_fp8_sdwa v[120:121], v33 src0_sel:WORD_1
	v_pk_fma_f32 v[110:111], v[88:89], v[118:119], v[110:111] op_sel:[1,0,0] op_sel_hi:[1,1,1]
	v_pk_fma_f32 v[112:113], v[88:89], v[120:121], v[112:113] op_sel:[1,0,0] op_sel_hi:[1,1,1]
	v_add_u32_e32 v159, v66, v156
	global_load_dwordx4 v[2:5], v159, s[38:39]
	v_add_u32_e32 v159, v67, v156
	global_load_dwordx4 v[6:9], v159, s[38:39]
	v_add_u32_e32 v159, v68, v156
	global_load_dwordx4 v[10:13], v159, s[38:39]
	v_add_u32_e32 v159, v69, v156
	global_load_dwordx4 v[14:17], v159, s[38:39]
	v_add_u32_e32 v159, v70, v156
	global_load_dwordx4 v[18:21], v159, s[38:39]
	v_add_u32_e32 v159, v71, v156
	global_load_dwordx4 v[22:25], v159, s[38:39]
	v_add_u32_e32 v159, v72, v156
	global_load_dwordx4 v[26:29], v159, s[38:39]
	v_add_u32_e32 v159, v73, v156
	global_load_dwordx4 v[30:33], v159, s[38:39]
	s_waitcnt vmcnt(11)
; DEV void phase_peer_expert(const Params& p, int layer, int M, bool final_, int part, char* smem) {
;     ...
;       const float c0 = coefs[st * 8 + g], c1 = coefs[st * 8 + 4 + g];
;       const f32x2 ca = (f32x2){c0, c0}, cb = (f32x2){c1, c1};
; #pragma unroll
;       for (int c = 0; c < 4; c++) {
; #pragma unroll
;         for (int d = 0; d < 4; d++) {
;           acc[c * 8 + d * 2 + 0] += ca * __builtin_amdgcn_cvt_pk_f32_fp8((int)cur[c][d], false);
;           acc[c * 8 + d * 2 + 1] += ca * __builtin_amdgcn_cvt_pk_f32_fp8((int)cur[c][d], true);
;           acc[c * 8 + d * 2 + 0] += cb * __builtin_amdgcn_cvt_pk_f32_fp8((int)cur[4 + c][d], false);
;           acc[c * 8 + d * 2 + 1] += cb * __builtin_amdgcn_cvt_pk_f32_fp8((int)cur[4 + c][d], true);
;         }
;       }
	v_cvt_pk_f32_fp8_e32 v[114:115], v34
	v_cvt_pk_f32_fp8_sdwa v[116:117], v34 src0_sel:WORD_1
	v_pk_fma_f32 v[98:99], v[90:91], v[114:115], v[98:99] op_sel_hi:[0,1,1]
	v_pk_fma_f32 v[100:101], v[90:91], v[116:117], v[100:101] op_sel_hi:[0,1,1]
	v_cvt_pk_f32_fp8_e32 v[118:119], v35
	v_cvt_pk_f32_fp8_sdwa v[120:121], v35 src0_sel:WORD_1
	v_pk_fma_f32 v[102:103], v[90:91], v[118:119], v[102:103] op_sel_hi:[0,1,1]
	v_pk_fma_f32 v[104:105], v[90:91], v[120:121], v[104:105] op_sel_hi:[0,1,1]
	v_cvt_pk_f32_fp8_e32 v[114:115], v36
	v_cvt_pk_f32_fp8_sdwa v[116:117], v36 src0_sel:WORD_1
	v_pk_fma_f32 v[106:107], v[90:91], v[114:115], v[106:107] op_sel_hi:[0,1,1]
	v_pk_fma_f32 v[108:109], v[90:91], v[116:117], v[108:109] op_sel_hi:[0,1,1]
	v_cvt_pk_f32_fp8_e32 v[118:119], v37
	v_cvt_pk_f32_fp8_sdwa v[120:121], v37 src0_sel:WORD_1
	v_pk_fma_f32 v[110:111], v[90:91], v[118:119], v[110:111] op_sel_hi:[0,1,1]
	v_pk_fma_f32 v[112:113], v[90:91], v[120:121], v[112:113] op_sel_hi:[0,1,1]
	v_cvt_pk_f32_fp8_e32 v[114:115], v38
	v_cvt_pk_f32_fp8_sdwa v[116:117], v38 src0_sel:WORD_1
	v_pk_fma_f32 v[98:99], v[90:91], v[114:115], v[98:99] op_sel:[1,0,0] op_sel_hi:[1,1,1]
	v_pk_fma_f32 v[100:101], v[90:91], v[116:117], v[100:101] op_sel:[1,0,0] op_sel_hi:[1,1,1]
	v_cvt_pk_f32_fp8_e32 v[118:119], v39
	v_cvt_pk_f32_fp8_sdwa v[120:121], v39 src0_sel:WORD_1
	v_pk_fma_f32 v[102:103], v[90:91], v[118:119], v[102:103] op_sel:[1,0,0] op_sel_hi:[1,1,1]
	v_pk_fma_f32 v[104:105], v[90:91], v[120:121], v[104:105] op_sel:[1,0,0] op_sel_hi:[1,1,1]
	v_cvt_pk_f32_fp8_e32 v[114:115], v40
	v_cvt_pk_f32_fp8_sdwa v[116:117], v40 src0_sel:WORD_1
	v_pk_fma_f32 v[106:107], v[90:91], v[114:115], v[106:107] op_sel:[1,0,0] op_sel_hi:[1,1,1]
	v_pk_fma_f32 v[108:109], v[90:91], v[116:117], v[108:109] op_sel:[1,0,0] op_sel_hi:[1,1,1]
	v_cvt_pk_f32_fp8_e32 v[118:119], v41
	v_cvt_pk_f32_fp8_sdwa v[120:121], v41 src0_sel:WORD_1
	v_pk_fma_f32 v[110:111], v[90:91], v[118:119], v[110:111] op_sel:[1,0,0] op_sel_hi:[1,1,1]
	v_pk_fma_f32 v[112:113], v[90:91], v[120:121], v[112:113] op_sel:[1,0,0] op_sel_hi:[1,1,1]
	v_cvt_pk_f32_fp8_e32 v[114:115], v42
	v_cvt_pk_f32_fp8_sdwa v[116:117], v42 src0_sel:WORD_1
	v_pk_fma_f32 v[98:99], v[92:93], v[114:115], v[98:99] op_sel_hi:[0,1,1]
	v_pk_fma_f32 v[100:101], v[92:93], v[116:117], v[100:101] op_sel_hi:[0,1,1]
	v_cvt_pk_f32_fp8_e32 v[118:119], v43
	v_cvt_pk_f32_fp8_sdwa v[120:121], v43 src0_sel:WORD_1
	v_pk_fma_f32 v[102:103], v[92:93], v[118:119], v[102:103] op_sel_hi:[0,1,1]
	v_pk_fma_f32 v[104:105], v[92:93], v[120:121], v[104:105] op_sel_hi:[0,1,1]
	v_cvt_pk_f32_fp8_e32 v[114:115], v44
	v_cvt_pk_f32_fp8_sdwa v[116:117], v44 src0_sel:WORD_1
	v_pk_fma_f32 v[106:107], v[92:93], v[114:115], v[106:107] op_sel_hi:[0,1,1]
	v_pk_fma_f32 v[108:109], v[92:93], v[116:117], v[108:109] op_sel_hi:[0,1,1]
	v_cvt_pk_f32_fp8_e32 v[118:119], v45
	v_cvt_pk_f32_fp8_sdwa v[120:121], v45 src0_sel:WORD_1
	v_pk_fma_f32 v[110:111], v[92:93], v[118:119], v[110:111] op_sel_hi:[0,1,1]
	v_pk_fma_f32 v[112:113], v[92:93], v[120:121], v[112:113] op_sel_hi:[0,1,1]
	v_cvt_pk_f32_fp8_e32 v[114:115], v46
	v_cvt_pk_f32_fp8_sdwa v[116:117], v46 src0_sel:WORD_1
	v_pk_fma_f32 v[98:99], v[92:93], v[114:115], v[98:99] op_sel:[1,0,0] op_sel_hi:[1,1,1]
	v_pk_fma_f32 v[100:101], v[92:93], v[116:117], v[100:101] op_sel:[1,0,0] op_sel_hi:[1,1,1]
	v_cvt_pk_f32_fp8_e32 v[118:119], v47
	v_cvt_pk_f32_fp8_sdwa v[120:121], v47 src0_sel:WORD_1
	v_pk_fma_f32 v[102:103], v[92:93], v[118:119], v[102:103] op_sel:[1,0,0] op_sel_hi:[1,1,1]
	v_pk_fma_f32 v[104:105], v[92:93], v[120:121], v[104:105] op_sel:[1,0,0] op_sel_hi:[1,1,1]
	v_cvt_pk_f32_fp8_e32 v[114:115], v48
	v_cvt_pk_f32_fp8_sdwa v[116:117], v48 src0_sel:WORD_1
	v_pk_fma_f32 v[106:107], v[92:93], v[114:115], v[106:107] op_sel:[1,0,0] op_sel_hi:[1,1,1]
	v_pk_fma_f32 v[108:109], v[92:93], v[116:117], v[108:109] op_sel:[1,0,0] op_sel_hi:[1,1,1]
	v_cvt_pk_f32_fp8_e32 v[118:119], v49
	v_cvt_pk_f32_fp8_sdwa v[120:121], v49 src0_sel:WORD_1
	v_pk_fma_f32 v[110:111], v[92:93], v[118:119], v[110:111] op_sel:[1,0,0] op_sel_hi:[1,1,1]
	v_pk_fma_f32 v[112:113], v[92:93], v[120:121], v[112:113] op_sel:[1,0,0] op_sel_hi:[1,1,1]
	v_cvt_pk_f32_fp8_e32 v[114:115], v50
	v_cvt_pk_f32_fp8_sdwa v[116:117], v50 src0_sel:WORD_1
	v_pk_fma_f32 v[98:99], v[94:95], v[114:115], v[98:99] op_sel_hi:[0,1,1]
	v_pk_fma_f32 v[100:101], v[94:95], v[116:117], v[100:101] op_sel_hi:[0,1,1]
	v_cvt_pk_f32_fp8_e32 v[118:119], v51
	v_cvt_pk_f32_fp8_sdwa v[120:121], v51 src0_sel:WORD_1
	v_pk_fma_f32 v[102:103], v[94:95], v[118:119], v[102:103] op_sel_hi:[0,1,1]
	v_pk_fma_f32 v[104:105], v[94:95], v[120:121], v[104:105] op_sel_hi:[0,1,1]
	v_cvt_pk_f32_fp8_e32 v[114:115], v52
	v_cvt_pk_f32_fp8_sdwa v[116:117], v52 src0_sel:WORD_1
	v_pk_fma_f32 v[106:107], v[94:95], v[114:115], v[106:107] op_sel_hi:[0,1,1]
	v_pk_fma_f32 v[108:109], v[94:95], v[116:117], v[108:109] op_sel_hi:[0,1,1]
	v_cvt_pk_f32_fp8_e32 v[118:119], v53
	v_cvt_pk_f32_fp8_sdwa v[120:121], v53 src0_sel:WORD_1
	v_pk_fma_f32 v[110:111], v[94:95], v[118:119], v[110:111] op_sel_hi:[0,1,1]
	v_pk_fma_f32 v[112:113], v[94:95], v[120:121], v[112:113] op_sel_hi:[0,1,1]
	v_cvt_pk_f32_fp8_e32 v[114:115], v54
	v_cvt_pk_f32_fp8_sdwa v[116:117], v54 src0_sel:WORD_1
	v_pk_fma_f32 v[98:99], v[94:95], v[114:115], v[98:99] op_sel:[1,0,0] op_sel_hi:[1,1,1]
	v_pk_fma_f32 v[100:101], v[94:95], v[116:117], v[100:101] op_sel:[1,0,0] op_sel_hi:[1,1,1]
	v_cvt_pk_f32_fp8_e32 v[118:119], v55
	v_cvt_pk_f32_fp8_sdwa v[120:121], v55 src0_sel:WORD_1
	v_pk_fma_f32 v[102:103], v[94:95], v[118:119], v[102:103] op_sel:[1,0,0] op_sel_hi:[1,1,1]
; DEV void phase_peer_expert(const Params& p, int layer, int M, bool final_, int part, char* smem) {
;     ...
;     __syncthreads();
; #pragma unroll
;     for (int i = 0; i < 32; i++) {
;       acc[i].x += __shfl_xor(acc[i].x, 16); acc[i].x += __shfl_xor(acc[i].x, 32);
;       acc[i].y += __shfl_xor(acc[i].y, 16); acc[i].y += __shfl_xor(acc[i].y, 32);
;     }
;     const int mr = (m < MM) ? (m >> 13) : 2;
;     const float* m5 = mod + (size_t)mr * 6144 + 5 * 1024;
;     float xn[16];
; #pragma unroll
;     for (int c = 0; c < 4; c++) {
;       if (c == g) {
; #pragma unroll
;         for (int i = 0; i < 8; i++) { xn[2 * i] = acc[c * 8 + i].x; xn[2 * i + 1] = acc[c * 8 + i].y; }
;       }
;     }
;     const int col = g * 256 + l16 * 16;
;     float ss = 0.f;
; #pragma unroll
;     for (int q = 0; q < 4; q++) {
;       float4 xa = *(const float4*)(X + (size_t)m * 1024 + col + q * 4);
;       float4 ma = *(const float4*)(m5 + col + q * 4);
;       xn[q * 4 + 0] = xa.x + ma.x * xn[q * 4 + 0]; xn[q * 4 + 1] = xa.y + ma.y * xn[q * 4 + 1];
;       xn[q * 4 + 2] = xa.z + ma.z * xn[q * 4 + 2]; xn[q * 4 + 3] = xa.w + ma.w * xn[q * 4 + 3];
;     }
; #pragma unroll
;     for (int i = 0; i < 16; i++) ss += xn[i] * xn[i];
	v_pk_fma_f32 v[104:105], v[94:95], v[120:121], v[104:105] op_sel:[1,0,0] op_sel_hi:[1,1,1]
	v_cvt_pk_f32_fp8_e32 v[114:115], v56
	v_cvt_pk_f32_fp8_sdwa v[116:117], v56 src0_sel:WORD_1
	v_pk_fma_f32 v[106:107], v[94:95], v[114:115], v[106:107] op_sel:[1,0,0] op_sel_hi:[1,1,1]
	v_pk_fma_f32 v[108:109], v[94:95], v[116:117], v[108:109] op_sel:[1,0,0] op_sel_hi:[1,1,1]
	v_cvt_pk_f32_fp8_e32 v[118:119], v57
	v_cvt_pk_f32_fp8_sdwa v[120:121], v57 src0_sel:WORD_1
	v_pk_fma_f32 v[110:111], v[94:95], v[118:119], v[110:111] op_sel:[1,0,0] op_sel_hi:[1,1,1]
	v_pk_fma_f32 v[112:113], v[94:95], v[120:121], v[112:113] op_sel:[1,0,0] op_sel_hi:[1,1,1]
	v_cvt_pk_f32_fp8_e32 v[114:115], v58
	v_cvt_pk_f32_fp8_sdwa v[116:117], v58 src0_sel:WORD_1
	v_pk_fma_f32 v[98:99], v[96:97], v[114:115], v[98:99] op_sel_hi:[0,1,1]
	v_pk_fma_f32 v[100:101], v[96:97], v[116:117], v[100:101] op_sel_hi:[0,1,1]
	v_cvt_pk_f32_fp8_e32 v[118:119], v59
	v_cvt_pk_f32_fp8_sdwa v[120:121], v59 src0_sel:WORD_1
	v_pk_fma_f32 v[102:103], v[96:97], v[118:119], v[102:103] op_sel_hi:[0,1,1]
	v_pk_fma_f32 v[104:105], v[96:97], v[120:121], v[104:105] op_sel_hi:[0,1,1]
	v_cvt_pk_f32_fp8_e32 v[114:115], v60
	v_cvt_pk_f32_fp8_sdwa v[116:117], v60 src0_sel:WORD_1
	v_pk_fma_f32 v[106:107], v[96:97], v[114:115], v[106:107] op_sel_hi:[0,1,1]
	v_pk_fma_f32 v[108:109], v[96:97], v[116:117], v[108:109] op_sel_hi:[0,1,1]
	v_cvt_pk_f32_fp8_e32 v[118:119], v61
	v_cvt_pk_f32_fp8_sdwa v[120:121], v61 src0_sel:WORD_1
	v_pk_fma_f32 v[110:111], v[96:97], v[118:119], v[110:111] op_sel_hi:[0,1,1]
	v_pk_fma_f32 v[112:113], v[96:97], v[120:121], v[112:113] op_sel_hi:[0,1,1]
	v_cvt_pk_f32_fp8_e32 v[114:115], v62
	v_cvt_pk_f32_fp8_sdwa v[116:117], v62 src0_sel:WORD_1
	v_pk_fma_f32 v[98:99], v[96:97], v[114:115], v[98:99] op_sel:[1,0,0] op_sel_hi:[1,1,1]
	v_pk_fma_f32 v[100:101], v[96:97], v[116:117], v[100:101] op_sel:[1,0,0] op_sel_hi:[1,1,1]
	v_cvt_pk_f32_fp8_e32 v[118:119], v63
	v_cvt_pk_f32_fp8_sdwa v[120:121], v63 src0_sel:WORD_1
	v_pk_fma_f32 v[102:103], v[96:97], v[118:119], v[102:103] op_sel:[1,0,0] op_sel_hi:[1,1,1]
	v_pk_fma_f32 v[104:105], v[96:97], v[120:121], v[104:105] op_sel:[1,0,0] op_sel_hi:[1,1,1]
	v_cvt_pk_f32_fp8_e32 v[114:115], v64
	v_cvt_pk_f32_fp8_sdwa v[116:117], v64 src0_sel:WORD_1
	v_pk_fma_f32 v[106:107], v[96:97], v[114:115], v[106:107] op_sel:[1,0,0] op_sel_hi:[1,1,1]
	v_pk_fma_f32 v[108:109], v[96:97], v[116:117], v[108:109] op_sel:[1,0,0] op_sel_hi:[1,1,1]
	v_cvt_pk_f32_fp8_e32 v[118:119], v65
	v_cvt_pk_f32_fp8_sdwa v[120:121], v65 src0_sel:WORD_1
	v_pk_fma_f32 v[110:111], v[96:97], v[118:119], v[110:111] op_sel:[1,0,0] op_sel_hi:[1,1,1]
	v_pk_fma_f32 v[112:113], v[96:97], v[120:121], v[112:113] op_sel:[1,0,0] op_sel_hi:[1,1,1]
	v_add_u32_e32 v159, v74, v156
	global_load_dwordx4 v[34:37], v159, s[38:39]
	v_add_u32_e32 v159, v75, v156
	global_load_dwordx4 v[38:41], v159, s[38:39]
	v_add_u32_e32 v159, v76, v156
	global_load_dwordx4 v[42:45], v159, s[38:39]
	v_add_u32_e32 v159, v77, v156
	global_load_dwordx4 v[46:49], v159, s[38:39]
	v_add_u32_e32 v159, v78, v156
	global_load_dwordx4 v[50:53], v159, s[38:39]
	v_add_u32_e32 v159, v79, v156
	global_load_dwordx4 v[54:57], v159, s[38:39]
	v_add_u32_e32 v159, v80, v156
	global_load_dwordx4 v[58:61], v159, s[38:39]
	v_add_u32_e32 v159, v81, v156
	global_load_dwordx4 v[62:65], v159, s[38:39]
	s_nop 0
	ds_write_b128 v169, v[98:101] offset:0
	ds_write_b128 v169, v[102:105] offset:128
	ds_write_b128 v169, v[106:109] offset:256
	ds_write_b128 v169, v[110:113] offset:384
	ds_read_b64 v[126:127], v170 offset:0
	ds_read_b64 v[128:129], v170 offset:512
	ds_read_b64 v[130:131], v170 offset:1024
	ds_read_b64 v[132:133], v170 offset:1536
	ds_read_b64 v[134:135], v170 offset:2048
	ds_read_b64 v[136:137], v170 offset:2560
	ds_read_b64 v[138:139], v170 offset:3072
	ds_read_b64 v[140:141], v170 offset:3584
	v_add_u32_e32 v160, s32, v172
	ds_read_b128 v[82:85], v160 offset:0
	ds_read_b128 v[86:89], v160 offset:16
	ds_read_b128 v[90:93], v160 offset:32
	ds_read_b128 v[94:97], v160 offset:48
	s_waitcnt lgkmcnt(4)
	v_pk_add_f32 v[126:127], v[126:127], v[128:129]
	v_pk_add_f32 v[130:131], v[130:131], v[132:133]
	v_pk_add_f32 v[134:135], v[134:135], v[136:137]
	v_pk_add_f32 v[138:139], v[138:139], v[140:141]
	s_nop 0
	v_pk_add_f32 v[126:127], v[126:127], v[130:131]
	v_pk_add_f32 v[134:135], v[134:135], v[138:139]
	s_nop 1
	v_pk_add_f32 v[126:127], v[126:127], v[134:135]
	s_waitcnt vmcnt(16)
	s_nop 0
	v_fmac_f32_e32 v122, v124, v126
	v_fmac_f32_e32 v123, v125, v127
	v_add_u32_e32 v173, s41, v168
	global_store_dwordx2 v173, v[122:123], s[0:1]
	v_mul_f32_e32 v174, v122, v122
	v_fmac_f32_e32 v174, v123, v123
	s_lshl_b32 s40, s18, 8
	v_add_u32_e32 v160, s40, v171
	ds_add_f32 v160, v174
	s_mov_b32 s18, s22
	s_mov_b32 s20, s28
	s_add_u32 s22, s22, 1
	s_cmp_lt_u32 s22, s8
	s_cbranch_scc1 .Lv_nx_ok
	s_mov_b32 s22, 0
	s_add_u32 s28, s28, 1
	s_cmp_lt_u32 s28, 8
	s_cbranch_scc1 .Lv_nx_ok
	s_mov_b32 s22, s18
	s_mov_b32 s28, s20
; DEV unsigned pack2(float a, float b) { f32x2 v = {a, b}; return __builtin_bit_cast(unsigned, __builtin_convertvector(v, bf2_t)); }
; DEV void phase_peer_expert(const Params& p, int layer, int M, bool final_, int part, char* smem) {
;     ...
;     if (!final_) {
; #pragma unroll
;       for (int q = 0; q < 4; q++)
;         *(float4*)(X + (size_t)m * 1024 + col + q * 4) = make_float4(xn[q * 4 + 0], xn[q * 4 + 1], xn[q * 4 + 2], xn[q * 4 + 3]);
;       ss = wave_sum(ss);
;       const float rinv = rsqrtf(ss * (1.f / 1024.f) + 1e-6f);
;       const float* ng = p.in[I_N1G] + (layer + 1) * 1024;
;       const float* nmod = WSP(float, S_MOD) + (size_t)(layer + 1) * 3 * 6144 + (size_t)mr * 6144;
;       unsigned hv[8];
; #pragma unroll
;       for (int q = 0; q < 4; q++) {
;         float4 g4 = *(const float4*)(ng + col + q * 4), sh = *(const float4*)(nmod + col + q * 4), sc = *(const float4*)(nmod + 1024 + col + q * 4);
;         hv[q * 2 + 0] = pack2(xn[q * 4 + 0] * rinv * g4.x * (1.f + sc.x) + sh.x, xn[q * 4 + 1] * rinv * g4.y * (1.f + sc.y) + sh.y);
;         hv[q * 2 + 1] = pack2(xn[q * 4 + 2] * rinv * g4.z * (1.f + sc.z) + sh.z, xn[q * 4 + 3] * rinv * g4.w * (1.f + sc.w) + sh.w);
;       }
;       bf16_t* hw = WSP(bf16_t, OFF_H) + (size_t)m * LDH + col;
;       *(uint4*)(hw) = make_uint4(hv[0], hv[1], hv[2], hv[3]);
;       *(uint4*)(hw + 8) = make_uint4(hv[4], hv[5], hv[6], hv[7]);
.Lv_nx_ok:
	s_lshl_b32 s40, s28, 21
	s_add_u32 s38, s14, s40
	s_addc_u32 s39, s15, 0
	s_lshl_b32 s32, s22, 9
	s_lshl_b32 s40, s18, 2
	s_add_u32 s40, s40, s9
	s_lshr_b32 s42, s40, 13
	s_min_u32 s42, s42, 2
	s_mul_i32 s42, s42, 0x6000
	s_lshl_b32 s41, s40, 12
	s_lshl_b32 s43, s20, 9
	s_add_u32 s41, s41, s43
	s_add_u32 s42, s42, s43
	v_add_u32_e32 v173, s41, v168
	global_load_dwordx2 v[122:123], v173, s[0:1]
	v_add_u32_e32 v174, s42, v168
	global_load_dwordx2 v[124:125], v174, s[16:17]
	v_add_u32_e32 v160, s32, v157
	ds_read_b128 v[66:69], v160 offset:0
	ds_read_b128 v[70:73], v160 offset:16
	ds_read_b128 v[74:77], v160 offset:32
	ds_read_b128 v[78:81], v160 offset:48
	s_sub_u32 s37, s37, 1
	s_cmp_lg_u32 s37, 0
	s_cbranch_scc1 .Lv_loop
	s_waitcnt vmcnt(0) lgkmcnt(0)
	v_mov_b32_e32 v2, 0x13b30
	ds_read_b64 v[2:3], v2
	v_mov_b32_e32 v4, 0x13bd0
	ds_read_b128 v[4:7], v4
	v_mov_b32_e32 v8, 0x13be0
	ds_read_b64 v[8:9], v8
	s_waitcnt lgkmcnt(0)
	v_readfirstlane_b32 s10, v2
	v_readfirstlane_b32 s11, v3
	v_readfirstlane_b32 s12, v4
	v_readfirstlane_b32 s13, v5
	v_readfirstlane_b32 s2, v8
	v_readfirstlane_b32 s3, v9
	s_add_u32 s10, s10, 0x1000
	s_addc_u32 s11, s11, 0
	s_add_u32 s16, s0, 0xbf52000
	s_addc_u32 s17, s1, 0
	s_add_u32 s14, s0, 0x4200000
	s_addc_u32 s15, s1, 0
	v_lshlrev_b32_e32 v173, 6, v162
	s_mov_b32 s18, 0
.Lv_tail:
	s_lshl_b32 s40, s18, 2
	s_add_u32 s40, s40, s9
	s_lshl_b32 s41, s40, 12
	v_add_u32_e32 v159, s41, v173
	global_load_dwordx4 v[2:5], v159, s[0:1] offset:0
	global_load_dwordx4 v[6:9], v159, s[0:1] offset:16
	global_load_dwordx4 v[10:13], v159, s[0:1] offset:32
	global_load_dwordx4 v[14:17], v159, s[0:1] offset:48
	s_lshl_b32 s42, s18, 8
	v_add_u32_e32 v160, s42, v171
	ds_read_b32 v174, v160
	s_cmp_eq_u32 s57, 20
	s_cbranch_scc1 .Lv_tail_final
	s_lshr_b32 s42, s40, 13
	s_min_u32 s42, s42, 2
	s_mul_i32 s42, s42, 0x6000
	v_add_u32_e32 v160, s42, v173
	global_load_dwordx4 v[18:21], v173, s[10:11] offset:0
	global_load_dwordx4 v[22:25], v173, s[10:11] offset:16
	global_load_dwordx4 v[26:29], v173, s[10:11] offset:32
	global_load_dwordx4 v[30:33], v173, s[10:11] offset:48
	global_load_dwordx4 v[34:37], v160, s[16:17] offset:0
	global_load_dwordx4 v[38:41], v160, s[16:17] offset:16
	global_load_dwordx4 v[42:45], v160, s[16:17] offset:32
	global_load_dwordx4 v[46:49], v160, s[16:17] offset:48
	v_add_u32_e32 v68, 0x1000, v160
	global_load_dwordx4 v[50:53], v68, s[16:17] offset:0
	global_load_dwordx4 v[54:57], v68, s[16:17] offset:16
	global_load_dwordx4 v[58:61], v68, s[16:17] offset:32
	global_load_dwordx4 v[62:65], v68, s[16:17] offset:48
	s_waitcnt lgkmcnt(0)
	s_nop 1
	v_add_f32_dpp v174, v174, v174 quad_perm:[1,0,3,2] row_mask:0xf bank_mask:0xf
	s_nop 1
	v_add_f32_dpp v174, v174, v174 quad_perm:[2,3,0,1] row_mask:0xf bank_mask:0xf
	s_nop 1
	v_add_f32_dpp v174, v174, v174 row_half_mirror row_mask:0xf bank_mask:0xf
	s_nop 1
	v_add_f32_dpp v174, v174, v174 row_mirror row_mask:0xf bank_mask:0xf
	ds_bpermute_b32 v66, v175, v174
	s_waitcnt lgkmcnt(0)
	v_add_f32_e32 v174, v174, v66
	ds_bpermute_b32 v66, v176, v174
	s_waitcnt lgkmcnt(0)
	v_add_f32_e32 v174, v174, v66
	v_fmamk_f32 v174, v174, 0x3a800000, v211
	s_nop 0
	v_rsq_f32_e32 v174, v174
	s_waitcnt vmcnt(0)
	v_mul_f32_e32 v2, v2, v174
	v_mul_f32_e32 v3, v3, v174
	v_mul_f32_e32 v4, v4, v174
	v_mul_f32_e32 v5, v5, v174
	v_mul_f32_e32 v6, v6, v174
	v_mul_f32_e32 v7, v7, v174
	v_mul_f32_e32 v8, v8, v174
	v_mul_f32_e32 v9, v9, v174
	v_mul_f32_e32 v10, v10, v174
	v_mul_f32_e32 v11, v11, v174
	v_mul_f32_e32 v12, v12, v174
	v_mul_f32_e32 v13, v13, v174
	v_mul_f32_e32 v14, v14, v174
	v_mul_f32_e32 v15, v15, v174
	v_mul_f32_e32 v16, v16, v174
	v_mul_f32_e32 v17, v17, v174
	v_mul_f32_e32 v2, v2, v18
	v_mul_f32_e32 v3, v3, v19
	v_mul_f32_e32 v4, v4, v20
	v_mul_f32_e32 v5, v5, v21
	v_mul_f32_e32 v6, v6, v22
	v_mul_f32_e32 v7, v7, v23
	v_mul_f32_e32 v8, v8, v24
	v_mul_f32_e32 v9, v9, v25
	v_mul_f32_e32 v10, v10, v26
	v_mul_f32_e32 v11, v11, v27
	v_mul_f32_e32 v12, v12, v28
	v_mul_f32_e32 v13, v13, v29
	v_mul_f32_e32 v14, v14, v30
	v_mul_f32_e32 v15, v15, v31
	v_mul_f32_e32 v16, v16, v32
	v_mul_f32_e32 v17, v17, v33
	v_add_f32_e32 v50, 1.0, v50
	v_add_f32_e32 v51, 1.0, v51
	v_add_f32_e32 v52, 1.0, v52
	v_add_f32_e32 v53, 1.0, v53
	v_add_f32_e32 v54, 1.0, v54
	v_add_f32_e32 v55, 1.0, v55
	v_add_f32_e32 v56, 1.0, v56
	v_add_f32_e32 v57, 1.0, v57
	v_add_f32_e32 v58, 1.0, v58
	v_add_f32_e32 v59, 1.0, v59
	v_add_f32_e32 v60, 1.0, v60
	v_add_f32_e32 v61, 1.0, v61
	v_add_f32_e32 v62, 1.0, v62
	v_add_f32_e32 v63, 1.0, v63
	v_add_f32_e32 v64, 1.0, v64
	v_add_f32_e32 v65, 1.0, v65
	v_fma_f32 v2, v2, v50, v34
	v_fma_f32 v3, v3, v51, v35
	v_fma_f32 v4, v4, v52, v36
	v_fma_f32 v5, v5, v53, v37
	v_fma_f32 v6, v6, v54, v38
	v_fma_f32 v7, v7, v55, v39
	v_fma_f32 v8, v8, v56, v40
	v_fma_f32 v9, v9, v57, v41
	v_fma_f32 v10, v10, v58, v42
	v_fma_f32 v11, v11, v59, v43
	v_fma_f32 v12, v12, v60, v44
	v_fma_f32 v13, v13, v61, v45
	v_fma_f32 v14, v14, v62, v46
	v_fma_f32 v15, v15, v63, v47
	v_fma_f32 v16, v16, v64, v48
	v_fma_f32 v17, v17, v65, v49
	v_cvt_pk_bf16_f32 v18, v2, v3
	v_cvt_pk_bf16_f32 v19, v4, v5
	v_cvt_pk_bf16_f32 v20, v6, v7
	v_cvt_pk_bf16_f32 v21, v8, v9
	v_cvt_pk_bf16_f32 v22, v10, v11
	v_cvt_pk_bf16_f32 v23, v12, v13
	v_cvt_pk_bf16_f32 v24, v14, v15
	v_cvt_pk_bf16_f32 v25, v16, v17
	s_mul_i32 s42, s40, 0x880
	v_lshl_add_u32 v160, v162, 5, s42
	global_store_dwordx4 v160, v[18:21], s[14:15]
	global_store_dwordx4 v160, v[22:25], s[14:15] offset:16
	s_branch .Lv_tail_next
; DEV void phase_peer_expert(const Params& p, int layer, int M, bool final_, int part, char* smem) {
;     ...
;     } else {
;       ss = wave_sum(ss);
;       const float rinv = rsqrtf(ss * (1.f / 1024.f) + 1e-6f);
;       const float* fg = p.in[I_FNG];
; #pragma unroll
;       for (int q = 0; q < 4; q++) {
;         float4 g4 = *(const float4*)(fg + col + q * 4);
;         *(float4*)(p.out + (size_t)m * 1024 + col + q * 4) = make_float4(xn[q * 4 + 0] * rinv * g4.x, xn[q * 4 + 1] * rinv * g4.y, xn[q * 4 + 2] * rinv * g4.z, xn[q * 4 + 3] * rinv * g4.w);
;       }
;     }
.Lv_tail_final:
	global_load_dwordx4 v[18:21], v173, s[12:13] offset:0
	global_load_dwordx4 v[22:25], v173, s[12:13] offset:16
	global_load_dwordx4 v[26:29], v173, s[12:13] offset:32
	global_load_dwordx4 v[30:33], v173, s[12:13] offset:48
	s_waitcnt lgkmcnt(0)
	s_nop 1
	v_add_f32_dpp v174, v174, v174 quad_perm:[1,0,3,2] row_mask:0xf bank_mask:0xf
	s_nop 1
	v_add_f32_dpp v174, v174, v174 quad_perm:[2,3,0,1] row_mask:0xf bank_mask:0xf
	s_nop 1
	v_add_f32_dpp v174, v174, v174 row_half_mirror row_mask:0xf bank_mask:0xf
	s_nop 1
	v_add_f32_dpp v174, v174, v174 row_mirror row_mask:0xf bank_mask:0xf
	ds_bpermute_b32 v66, v175, v174
	s_waitcnt lgkmcnt(0)
	v_add_f32_e32 v174, v174, v66
	ds_bpermute_b32 v66, v176, v174
	s_waitcnt lgkmcnt(0)
	v_add_f32_e32 v174, v174, v66
	v_fmamk_f32 v174, v174, 0x3a800000, v211
	s_nop 0
	v_rsq_f32_e32 v174, v174
	s_waitcnt vmcnt(0)
	v_mul_f32_e32 v2, v2, v174
	v_mul_f32_e32 v3, v3, v174
	v_mul_f32_e32 v4, v4, v174
	v_mul_f32_e32 v5, v5, v174
	v_mul_f32_e32 v6, v6, v174
	v_mul_f32_e32 v7, v7, v174
	v_mul_f32_e32 v8, v8, v174
	v_mul_f32_e32 v9, v9, v174
	v_mul_f32_e32 v10, v10, v174
	v_mul_f32_e32 v11, v11, v174
	v_mul_f32_e32 v12, v12, v174
	v_mul_f32_e32 v13, v13, v174
	v_mul_f32_e32 v14, v14, v174
	v_mul_f32_e32 v15, v15, v174
	v_mul_f32_e32 v16, v16, v174
	v_mul_f32_e32 v17, v17, v174
	v_mul_f32_e32 v2, v2, v18
	v_mul_f32_e32 v3, v3, v19
	v_mul_f32_e32 v4, v4, v20
	v_mul_f32_e32 v5, v5, v21
	v_mul_f32_e32 v6, v6, v22
	v_mul_f32_e32 v7, v7, v23
	v_mul_f32_e32 v8, v8, v24
	v_mul_f32_e32 v9, v9, v25
	v_mul_f32_e32 v10, v10, v26
	v_mul_f32_e32 v11, v11, v27
	v_mul_f32_e32 v12, v12, v28
	v_mul_f32_e32 v13, v13, v29
	v_mul_f32_e32 v14, v14, v30
	v_mul_f32_e32 v15, v15, v31
	v_mul_f32_e32 v16, v16, v32
	v_mul_f32_e32 v17, v17, v33
	global_store_dwordx4 v159, v[2:5], s[2:3] offset:0
	global_store_dwordx4 v159, v[6:9], s[2:3] offset:16
	global_store_dwordx4 v159, v[10:13], s[2:3] offset:32
	global_store_dwordx4 v159, v[14:17], s[2:3] offset:48
.Lv_tail_next:
	s_add_u32 s18, s18, 1
	s_cmp_lt_u32 s18, s8
	s_cbranch_scc1 .Lv_tail
	s_waitcnt vmcnt(0)
	s_cmp_eq_u32 s57, 20
	s_cbranch_scc1 .Lpeer_to_next
	s_branch .Lpeer_grid_barrier
.Lpeer_to_next:
	s_branch .LBB0_10
.LBB0_601:
	v_readlane_b32 s28, v254, 0
	s_mov_b64 s[2:3], 0
	s_mov_b64 s[0:1], -1
	s_movk_i32 s19, 0x880
	s_mov_b64 s[46:47], 0x3000
	s_mov_b64 s[48:49], 0x4000
	s_movk_i32 s21, 0x2000
	v_readlane_b32 s29, v254, 1

; DEV void phase_prep(const Params& p, char* smem) {
;     ...
;       const float* src = (isv ? p.in[I_PV] : p.in[I_PU]) + (size_t)rowb * 1024 + lane * 16;
;       float4 v[4][4];
; #pragma unroll
;       for (int r = 0; r < 4; r++)
; #pragma unroll
;         for (int q = 0; q < 4; q++) v[r][q] = *(const float4*)(src + (size_t)r * 1024 + q * 4);
; #pragma unroll
;       for (int r = 0; r < 4; r++) {
;         float mx = 0.f;
; #pragma unroll
;         for (int q = 0; q < 4; q++) mx = fmaxf(mx, fmaxf(fmaxf(fabsf(v[r][q].x), fabsf(v[r][q].y)), fmaxf(fabsf(v[r][q].z), fabsf(v[r][q].w))));
; #pragma unroll
;         for (int o = 32; o > 0; o >>= 1) mx = fmaxf(mx, __shfl_xor(mx, o));
;         mx = fmaxf(mx, 1e-30f);
;         const float sc = exp2f(floorf(log2f(384.f / mx)));
;         unsigned ow[4];
; #pragma unroll
;         for (int q = 0; q < 4; q++) {
;           int t = __builtin_amdgcn_cvt_pk_fp8_f32(v[r][q].x * sc, v[r][q].y * sc, 0, false);
;           t = __builtin_amdgcn_cvt_pk_fp8_f32(v[r][q].z * sc, v[r][q].w * sc, t, true);
;           ow[q] = (unsigned)t;
;         }
;         const int row = rowb + r; const int l = row >> 14, e = row & 16383;
;         unsigned char* dst = isv ? (l ? WSP(unsigned char, OFF_V1) : WSP(unsigned char, OFF_V0)) : (l ? WSP(unsigned char, OFF_U1) : WSP(unsigned char, OFF_U0));
;         *(uint4*)(dst + (size_t)e * 1024 + lane * 16) = make_uint4(ow[0], ow[1], ow[2], ow[3]);
.LBB0_1096:
	s_andn2_b64 vcc, exec, s[12:13]
	s_cbranch_vccnz .LBB0_1106
	s_cmpk_gt_u32 s49, 0x3bdf
	v_mov_b32_e32 v0, v195
	s_cselect_b64 s[40:41], -1, 0
	s_and_b64 s[12:13], s[40:41], exec
	v_and_b32_e32 v68, 63, v0
	v_mov_b32_e32 v0, v195
	s_movk_i32 s12, 0xc420
	s_cselect_b32 s12, s12, 0xffffcc20
	v_ashrrev_i32_e32 v0, 4, v0
	s_add_i32 s12, s12, s49
	v_and_b32_e32 v0, -4, v0
	v_lshl_add_u32 v66, s12, 4, v0
	s_and_b64 s[12:13], s[40:41], exec
	v_readlane_b32 s12, v253, 60
	v_readlane_b32 s13, v253, 62
	s_cselect_b32 s13, s13, s12
	v_readlane_b32 s12, v253, 59
	v_readlane_b32 s16, v253, 61
	v_ashrrev_i32_e32 v67, 31, v66
	s_cselect_b32 s12, s16, s12
	v_lshlrev_b64 v[2:3], 12, v[66:67]
	v_lshl_add_u64 v[2:3], s[12:13], 0, v[2:3]
	v_lshlrev_b32_e32 v4, 6, v68
	v_mov_b32_e32 v5, v1
	v_lshl_add_u64 v[2:3], v[2:3], 0, v[4:5]
	global_load_dwordx4 v[50:53], v[2:3], off offset:48
	global_load_dwordx4 v[54:57], v[2:3], off offset:32
	global_load_dwordx4 v[58:61], v[2:3], off offset:16
	global_load_dwordx4 v[62:65], v[2:3], off
	s_mov_b64 s[12:13], 0x1000
	v_add_co_u32_e32 v6, vcc, s57, v2
	v_lshl_add_u64 v[4:5], v[2:3], 0, s[12:13]
	s_nop 0
	v_addc_co_u32_e32 v7, vcc, 0, v3, vcc
	s_mov_b64 s[12:13], 0x2000
	global_load_dwordx4 v[46:49], v[6:7], off offset:-4096
	global_load_dwordx4 v[34:37], v[4:5], off offset:48
	global_load_dwordx4 v[38:41], v[4:5], off offset:32
	global_load_dwordx4 v[42:45], v[4:5], off offset:16
	v_lshl_add_u64 v[4:5], v[2:3], 0, s[12:13]
	s_movk_i32 s12, 0x3000
	v_lshl_add_u64 v[10:11], v[2:3], 0, s[20:21]
	v_add_co_u32_e32 v2, vcc, s12, v2
	s_movk_i32 s12, 0x4000
	v_and_b32_e32 v67, 0x3ffc, v66
	v_cmp_gt_u32_e64 s[42:43], s12, v66
	v_lshrrev_b32_e32 v66, 13, v66
	v_cndmask_b32_e64 v69, 0, 1, s[40:41]
	v_and_b32_e32 v66, 0x3fffe, v66
	v_lshlrev_b32_e32 v0, 4, v68
	v_cmp_eq_u32_e64 s[38:39], 0, v68
	v_or_b32_e32 v66, v66, v69
	v_lshrrev_b32_e32 v69, 3, v68
	v_and_b32_e32 v0, 0x70, v0
	v_lshl_or_b32 v0, v69, 21, v0
	v_addc_co_u32_e32 v3, vcc, 0, v3, vcc
	global_load_dwordx4 v[30:33], v[6:7], off
	global_load_dwordx4 v[18:21], v[4:5], off offset:48
	global_load_dwordx4 v[22:25], v[4:5], off offset:32
	global_load_dwordx4 v[26:29], v[4:5], off offset:16
	global_load_dwordx4 v[14:17], v[2:3], off
	s_nop 0
	global_load_dwordx4 v[2:5], v[10:11], off offset:48
	global_load_dwordx4 v[6:9], v[10:11], off offset:32
	s_nop 0
	global_load_dwordx4 v[10:13], v[10:11], off offset:16
	s_mov_b32 s12, 0xda24260
	s_mov_b32 s16, 0x43c00000
	v_lshlrev_b32_e32 v66, 14, v66
	s_waitcnt vmcnt(15)
	v_max_f32_e64 v71, |v52|, |v52|
	s_waitcnt vmcnt(13)
	v_max_f32_e64 v70, |v60|, |v60|
	s_waitcnt vmcnt(12)
	v_max_f32_e64 v68, |v65|, |v65|
	v_max_f32_e64 v69, |v64|, |v64|
	v_max_f32_e32 v68, v69, v68
	v_max_f32_e64 v69, |v61|, |v61|
	v_max_f32_e32 v69, v70, v69
	v_max3_f32 v68, |v62|, |v63|, v68
	v_max3_f32 v69, |v58|, |v59|, v69
	v_max3_f32 v68, v68, 0, v69
	v_max_f32_e64 v69, |v57|, |v57|
	v_max_f32_e64 v70, |v56|, |v56|
	v_max_f32_e32 v69, v70, v69
	v_max_f32_e64 v70, |v53|, |v53|
	v_max_f32_e32 v70, v71, v70
	v_max3_f32 v69, |v54|, |v55|, v69
	v_max3_f32 v70, |v50|, |v51|, v70
	v_max3_f32 v69, v68, v69, v70
	v_xor_b32_e32 v68, 32, v216
	v_cmp_lt_i32_e32 vcc, v68, v218
	s_nop 1
	v_cndmask_b32_e32 v68, v216, v68, vcc
	v_lshlrev_b32_e32 v68, 2, v68
	ds_bpermute_b32 v70, v68, v69
	s_waitcnt lgkmcnt(0)
	v_max_f32_e32 v70, v70, v70
	v_max_f32_e32 v70, v69, v70
	v_xor_b32_e32 v69, 16, v216
	v_cmp_lt_i32_e32 vcc, v69, v218
	s_nop 1
	v_cndmask_b32_e32 v69, v216, v69, vcc
	v_lshlrev_b32_e32 v69, 2, v69
	ds_bpermute_b32 v71, v69, v70
	v_cmp_lt_i32_e32 vcc, v221, v218
	s_waitcnt lgkmcnt(0)
	v_max_f32_e32 v71, v71, v71
	v_max_f32_e32 v71, v70, v71
	v_cndmask_b32_e32 v70, v216, v221, vcc
	v_lshlrev_b32_e32 v70, 2, v70
	ds_bpermute_b32 v72, v70, v71
	v_cmp_lt_i32_e32 vcc, v220, v218
	s_waitcnt lgkmcnt(0)
	v_max_f32_e32 v72, v72, v72
	v_max_f32_e32 v72, v71, v72
	v_cndmask_b32_e32 v71, v216, v220, vcc
	v_lshlrev_b32_e32 v71, 2, v71
	ds_bpermute_b32 v73, v71, v72
	v_cmp_lt_i32_e32 vcc, v219, v218
	s_waitcnt lgkmcnt(0)
	v_max_f32_e32 v73, v73, v73
	v_max_f32_e32 v73, v72, v73
	v_cndmask_b32_e32 v72, v216, v219, vcc
	v_lshlrev_b32_e32 v72, 2, v72
	ds_bpermute_b32 v74, v72, v73
	v_cmp_lt_i32_e32 vcc, v217, v218
	s_waitcnt lgkmcnt(0)
	v_max_f32_e32 v74, v74, v74
	v_max_f32_e32 v74, v73, v74
	v_cndmask_b32_e32 v73, v216, v217, vcc
	v_lshlrev_b32_e32 v73, 2, v73
	ds_bpermute_b32 v75, v73, v74
	s_waitcnt lgkmcnt(0)
	v_max3_f32 v74, v74, v75, s12
	v_div_scale_f32 v75, s[12:13], v74, v74, s16
	v_rcp_f32_e32 v76, v75
	s_mov_b32 s12, 0x800000
	v_fma_f32 v77, -v75, v76, 1.0
	v_fmac_f32_e32 v76, v77, v76
	v_div_scale_f32 v77, vcc, s16, v74, s16
	v_mul_f32_e32 v78, v77, v76
	v_fma_f32 v79, -v75, v78, v77
	v_fmac_f32_e32 v78, v79, v76
	v_fma_f32 v75, -v75, v78, v77
	v_div_fmas_f32 v75, v75, v76, v78
	v_div_fixup_f32 v74, v75, v74, s16
	v_cmp_gt_f32_e32 vcc, s12, v74
	s_mov_b32 s12, 0xc2fc0000
	s_nop 0
	v_cndmask_b32_e64 v75, 0, 32, vcc
	v_ldexp_f32 v74, v74, v75
	v_log_f32_e32 v74, v74
	v_cndmask_b32_e32 v75, 0, v250, vcc
	v_sub_f32_e32 v74, v74, v75
	v_floor_f32_e32 v74, v74
	v_cmp_gt_f32_e32 vcc, s12, v74
	v_readlane_b32 s12, v254, 0
	v_readlane_b32 s13, v254, 1
	v_cndmask_b32_e32 v75, 0, v251, vcc
	v_add_f32_e32 v74, v74, v75
	v_exp_f32_e32 v74, v74
	v_cndmask_b32_e32 v75, 0, v230, vcc
	v_ldexp_f32 v74, v74, v75
	v_mul_f32_e32 v75, v62, v74
	v_mul_f32_e32 v63, v63, v74
	v_mov_b32_e32 v62, v1
	v_cvt_pk_fp8_f32 v62, v75, v63
	v_mul_f32_e32 v63, v64, v74
	v_mul_f32_e32 v64, v65, v74
	v_mul_f32_e32 v50, v50, v74
	v_mul_f32_e32 v51, v51, v74
	v_mov_b32_e32 v65, v1
	v_cvt_pk_fp8_f32 v62, v63, v64 op_sel:[0,0,1]
	v_mul_f32_e32 v58, v58, v74
	v_mul_f32_e32 v59, v59, v74
	v_mov_b32_e32 v63, v1
	v_mul_f32_e32 v54, v54, v74
	v_mul_f32_e32 v55, v55, v74
	v_mov_b32_e32 v64, v1
	v_cvt_pk_fp8_f32 v65, v50, v51
	v_cvt_pk_fp8_f32 v63, v58, v59
	v_cvt_pk_fp8_f32 v64, v54, v55
	v_mul_f32_e32 v50, v52, v74
	v_mul_f32_e32 v51, v53, v74
	v_mul_f32_e32 v58, v60, v74
	v_mul_f32_e32 v59, v61, v74
	v_mul_f32_e32 v54, v56, v74
	v_mul_f32_e32 v55, v57, v74
	v_cvt_pk_fp8_f32 v65, v50, v51 op_sel:[0,0,1]
	v_cndmask_b32_e64 v50, v212, v224, s[42:43]
	v_cndmask_b32_e64 v51, v228, v229, s[42:43]
	v_cvt_pk_fp8_f32 v63, v58, v59 op_sel:[0,0,1]
	v_cvt_pk_fp8_f32 v64, v54, v55 op_sel:[0,0,1]
	v_cndmask_b32_e64 v50, v51, v50, s[40:41]
	v_mov_b32_e32 v51, v1
	v_lshl_add_u64 v[50:51], s[12:13], 0, v[50:51]
	v_lshlrev_b32_e32 v52, 7, v67
	v_mov_b32_e32 v53, v1
	v_lshl_add_u64 v[52:53], v[50:51], 0, v[52:53]
	v_lshl_add_u64 v[52:53], v[52:53], 0, v[0:1]
	global_store_dwordx4 v[52:53], v[62:65], off
	s_and_saveexec_b64 s[12:13], s[38:39]
	s_cbranch_execz .LBB0_1099
; DEV void phase_prep(const Params& p, char* smem) {
;     ...
;       for (int r = 0; r < 4; r++) {
;         float mx = 0.f;
; #pragma unroll
;         for (int q = 0; q < 4; q++) mx = fmaxf(mx, fmaxf(fmaxf(fabsf(v[r][q].x), fabsf(v[r][q].y)), fmaxf(fabsf(v[r][q].z), fabsf(v[r][q].w))));
; #pragma unroll
;         for (int o = 32; o > 0; o >>= 1) mx = fmaxf(mx, __shfl_xor(mx, o));
;         mx = fmaxf(mx, 1e-30f);
;         const float sc = exp2f(floorf(log2f(384.f / mx)));
;         unsigned ow[4];
; #pragma unroll
;         for (int q = 0; q < 4; q++) {
;           int t = __builtin_amdgcn_cvt_pk_fp8_f32(v[r][q].x * sc, v[r][q].y * sc, 0, false);
;           t = __builtin_amdgcn_cvt_pk_fp8_f32(v[r][q].z * sc, v[r][q].w * sc, t, true);
;           ow[q] = (unsigned)t;
;         }
;         const int row = rowb + r; const int l = row >> 14, e = row & 16383;
;         unsigned char* dst = isv ? (l ? WSP(unsigned char, OFF_V1) : WSP(unsigned char, OFF_V0)) : (l ? WSP(unsigned char, OFF_U1) : WSP(unsigned char, OFF_U0));
;         *(uint4*)(dst + (size_t)e * 1024 + lane * 16) = make_uint4(ow[0], ow[1], ow[2], ow[3]);
;         if (lane == 0) WSP(float, S_UVSC)[(l * 2 + isv) * 16384 + e] = 1.f / sc;
	v_div_scale_f32 v52, s[16:17], v74, v74, 1.0
	v_rcp_f32_e32 v53, v52
	v_div_scale_f32 v54, vcc, 1.0, v74, 1.0
	v_fma_f32 v55, -v52, v53, 1.0
	v_fmac_f32_e32 v53, v55, v53
	v_mul_f32_e32 v55, v54, v53
	v_fma_f32 v56, -v52, v55, v54
	v_fmac_f32_e32 v55, v56, v53
	v_fma_f32 v52, -v52, v55, v54
	v_div_fmas_f32 v52, v52, v53, v55
	v_div_fixup_f32 v54, v52, v74, 1.0
	v_or_b32_e32 v52, v66, v67
	v_ashrrev_i32_e32 v53, 31, v52
	v_lshl_add_u64 v[52:53], v[52:53], 2, s[8:9]
	global_store_dword v[52:53], v54, off
.LBB0_1099:
	s_or_b64 exec, exec, s[12:13]
	s_waitcnt vmcnt(12)
	v_max_f32_e64 v52, |v49|, |v49|
	v_max_f32_e64 v53, |v48|, |v48|
	v_max_f32_e32 v52, v53, v52
	s_waitcnt vmcnt(9)
	v_max_f32_e64 v53, |v45|, |v45|
	v_max_f32_e64 v54, |v44|, |v44|
	v_max_f32_e32 v53, v54, v53
	v_max3_f32 v52, |v46|, |v47|, v52
	v_max3_f32 v53, |v42|, |v43|, v53
	v_max3_f32 v52, v52, 0, v53
	v_max_f32_e64 v53, |v41|, |v41|
	v_max_f32_e64 v54, |v40|, |v40|
	v_max_f32_e32 v53, v54, v53
	v_max_f32_e64 v54, |v37|, |v37|
	v_max_f32_e64 v55, |v36|, |v36|
	v_max_f32_e32 v54, v55, v54
	v_max3_f32 v53, |v38|, |v39|, v53
	v_max3_f32 v54, |v34|, |v35|, v54
	v_max3_f32 v52, v52, v53, v54
	ds_bpermute_b32 v53, v68, v52
	s_mov_b32 s12, 0xda24260
	s_mov_b32 s16, 0x43c00000
	s_waitcnt lgkmcnt(0)
	v_max_f32_e32 v53, v53, v53
	v_max_f32_e32 v52, v52, v53
	ds_bpermute_b32 v53, v69, v52
	s_waitcnt lgkmcnt(0)
	v_max_f32_e32 v53, v53, v53
	v_max_f32_e32 v52, v52, v53
	ds_bpermute_b32 v53, v70, v52
	s_waitcnt lgkmcnt(0)
	v_max_f32_e32 v53, v53, v53
	v_max_f32_e32 v52, v52, v53
	ds_bpermute_b32 v53, v71, v52
	s_waitcnt lgkmcnt(0)
	v_max_f32_e32 v53, v53, v53
	v_max_f32_e32 v52, v52, v53
	ds_bpermute_b32 v53, v72, v52
	s_waitcnt lgkmcnt(0)
	v_max_f32_e32 v53, v53, v53
	v_max_f32_e32 v52, v52, v53
	ds_bpermute_b32 v53, v73, v52
	s_waitcnt lgkmcnt(0)
	v_max3_f32 v52, v52, v53, s12
	v_div_scale_f32 v53, s[12:13], v52, v52, s16
	v_rcp_f32_e32 v54, v53
	v_div_scale_f32 v55, vcc, s16, v52, s16
	s_mov_b32 s12, 0x800000
	v_fma_f32 v56, -v53, v54, 1.0
	v_fmac_f32_e32 v54, v56, v54
	v_mul_f32_e32 v56, v55, v54
	v_fma_f32 v57, -v53, v56, v55
	v_fmac_f32_e32 v56, v57, v54
	v_fma_f32 v53, -v53, v56, v55
	v_div_fmas_f32 v53, v53, v54, v56
	v_div_fixup_f32 v52, v53, v52, s16
	v_cmp_gt_f32_e32 vcc, s12, v52
	s_mov_b32 s12, 0xc2fc0000
	v_mov_b32_e32 v54, v1
	v_cndmask_b32_e64 v53, 0, 32, vcc
	v_ldexp_f32 v52, v52, v53
	v_log_f32_e32 v52, v52
	v_cndmask_b32_e32 v53, 0, v250, vcc
	v_mov_b32_e32 v55, v1
	v_mov_b32_e32 v56, v1
	v_sub_f32_e32 v52, v52, v53
	v_floor_f32_e32 v52, v52
	v_cmp_gt_f32_e32 vcc, s12, v52
	v_mov_b32_e32 v57, v1
	s_nop 0
	v_cndmask_b32_e32 v53, 0, v251, vcc
	v_add_f32_e32 v52, v52, v53
	v_exp_f32_e32 v52, v52
	v_cndmask_b32_e32 v53, 0, v230, vcc
	v_ldexp_f32 v52, v52, v53
	v_mul_f32_e32 v46, v46, v52
	v_mul_f32_e32 v47, v47, v52
	v_mul_f32_e32 v42, v42, v52
	v_mul_f32_e32 v43, v43, v52
	v_mul_f32_e32 v38, v38, v52
	v_mul_f32_e32 v39, v39, v52
	v_mul_f32_e32 v34, v34, v52
	v_mul_f32_e32 v35, v35, v52
	v_cvt_pk_fp8_f32 v54, v46, v47
	v_cvt_pk_fp8_f32 v55, v42, v43
	v_cvt_pk_fp8_f32 v56, v38, v39
	v_cvt_pk_fp8_f32 v57, v34, v35
	v_mul_f32_e32 v48, v48, v52
	v_mul_f32_e32 v49, v49, v52
	v_mul_f32_e32 v44, v44, v52
	v_mul_f32_e32 v45, v45, v52
	v_mul_f32_e32 v38, v40, v52
	v_mul_f32_e32 v39, v41, v52
	v_mul_f32_e32 v34, v36, v52
	v_mul_f32_e32 v35, v37, v52
	v_cvt_pk_fp8_f32 v54, v48, v49 op_sel:[0,0,1]
	v_cvt_pk_fp8_f32 v55, v44, v45 op_sel:[0,0,1]
	v_cvt_pk_fp8_f32 v56, v38, v39 op_sel:[0,0,1]
	v_cvt_pk_fp8_f32 v57, v34, v35 op_sel:[0,0,1]
	v_or_b32_e32 v34, 1, v67
	v_lshlrev_b32_e32 v36, 7, v34
	v_mov_b32_e32 v37, v1
	v_lshl_add_u64 v[36:37], v[50:51], 0, v[36:37]
	v_lshl_add_u64 v[36:37], v[36:37], 0, v[0:1]
	global_store_dwordx4 v[36:37], v[54:57], off
	s_and_saveexec_b64 s[12:13], s[38:39]
	s_cbranch_execz .LBB0_1101
	v_div_scale_f32 v35, s[16:17], v52, v52, 1.0
	v_rcp_f32_e32 v36, v35
	v_div_scale_f32 v37, vcc, 1.0, v52, 1.0
	v_or_b32_e32 v34, v66, v34
	v_fma_f32 v38, -v35, v36, 1.0
	v_fmac_f32_e32 v36, v38, v36
	v_mul_f32_e32 v38, v37, v36
	v_fma_f32 v39, -v35, v38, v37
	v_fmac_f32_e32 v38, v39, v36
	v_fma_f32 v35, -v35, v38, v37
	v_div_fmas_f32 v35, v35, v36, v38
	v_div_fixup_f32 v36, v35, v52, 1.0
	v_ashrrev_i32_e32 v35, 31, v34
	v_lshl_add_u64 v[34:35], v[34:35], 2, s[8:9]
	global_store_dword v[34:35], v36, off
; DEV void phase_prep(const Params& p, char* smem) {
;     ...
;       for (int r = 0; r < 4; r++) {
;         float mx = 0.f;
; #pragma unroll
;         for (int q = 0; q < 4; q++) mx = fmaxf(mx, fmaxf(fmaxf(fabsf(v[r][q].x), fabsf(v[r][q].y)), fmaxf(fabsf(v[r][q].z), fabsf(v[r][q].w))));
; #pragma unroll
;         for (int o = 32; o > 0; o >>= 1) mx = fmaxf(mx, __shfl_xor(mx, o));
;         mx = fmaxf(mx, 1e-30f);
;         const float sc = exp2f(floorf(log2f(384.f / mx)));
;         unsigned ow[4];
; #pragma unroll
;         for (int q = 0; q < 4; q++) {
;           int t = __builtin_amdgcn_cvt_pk_fp8_f32(v[r][q].x * sc, v[r][q].y * sc, 0, false);
;           t = __builtin_amdgcn_cvt_pk_fp8_f32(v[r][q].z * sc, v[r][q].w * sc, t, true);
;           ow[q] = (unsigned)t;
;         }
;         const int row = rowb + r; const int l = row >> 14, e = row & 16383;
;         unsigned char* dst = isv ? (l ? WSP(unsigned char, OFF_V1) : WSP(unsigned char, OFF_V0)) : (l ? WSP(unsigned char, OFF_U1) : WSP(unsigned char, OFF_U0));
;         *(uint4*)(dst + (size_t)e * 1024 + lane * 16) = make_uint4(ow[0], ow[1], ow[2], ow[3]);
;         if (lane == 0) WSP(float, S_UVSC)[(l * 2 + isv) * 16384 + e] = 1.f / sc;
.LBB0_1101:
	s_or_b64 exec, exec, s[12:13]
	s_waitcnt vmcnt(9)
	v_max_f32_e64 v34, |v33|, |v33|
	v_max_f32_e64 v35, |v32|, |v32|
	v_max_f32_e32 v34, v35, v34
	s_waitcnt vmcnt(6)
	v_max_f32_e64 v35, |v29|, |v29|
	v_max_f32_e64 v36, |v28|, |v28|
	v_max_f32_e32 v35, v36, v35
	v_max3_f32 v34, |v30|, |v31|, v34
	v_max3_f32 v35, |v26|, |v27|, v35
	v_max3_f32 v34, v34, 0, v35
	v_max_f32_e64 v35, |v25|, |v25|
	v_max_f32_e64 v36, |v24|, |v24|
	v_max_f32_e32 v35, v36, v35
	v_max_f32_e64 v36, |v21|, |v21|
	v_max_f32_e64 v37, |v20|, |v20|
	v_max_f32_e32 v36, v37, v36
	v_max3_f32 v35, |v22|, |v23|, v35
	v_max3_f32 v36, |v18|, |v19|, v36
	v_max3_f32 v34, v34, v35, v36
	ds_bpermute_b32 v35, v68, v34
	s_mov_b32 s12, 0xda24260
	s_mov_b32 s16, 0x43c00000
	s_waitcnt lgkmcnt(0)
	v_max_f32_e32 v35, v35, v35
	v_max_f32_e32 v34, v34, v35
	ds_bpermute_b32 v35, v69, v34
	s_waitcnt lgkmcnt(0)
	v_max_f32_e32 v35, v35, v35
	v_max_f32_e32 v34, v34, v35
	ds_bpermute_b32 v35, v70, v34
	s_waitcnt lgkmcnt(0)
	v_max_f32_e32 v35, v35, v35
	v_max_f32_e32 v34, v34, v35
	ds_bpermute_b32 v35, v71, v34
	s_waitcnt lgkmcnt(0)
	v_max_f32_e32 v35, v35, v35
	v_max_f32_e32 v34, v34, v35
	ds_bpermute_b32 v35, v72, v34
	s_waitcnt lgkmcnt(0)
	v_max_f32_e32 v35, v35, v35
	v_max_f32_e32 v34, v34, v35
	ds_bpermute_b32 v35, v73, v34
	s_waitcnt lgkmcnt(0)
	v_max3_f32 v34, v34, v35, s12
	v_div_scale_f32 v35, s[12:13], v34, v34, s16
	v_rcp_f32_e32 v36, v35
	v_div_scale_f32 v37, vcc, s16, v34, s16
	s_mov_b32 s12, 0x800000
	v_fma_f32 v38, -v35, v36, 1.0
	v_fmac_f32_e32 v36, v38, v36
	v_mul_f32_e32 v38, v37, v36
	v_fma_f32 v39, -v35, v38, v37
	v_fmac_f32_e32 v38, v39, v36
	v_fma_f32 v35, -v35, v38, v37
	v_div_fmas_f32 v35, v35, v36, v38
	v_div_fixup_f32 v34, v35, v34, s16
	v_cmp_gt_f32_e32 vcc, s12, v34
	s_mov_b32 s12, 0xc2fc0000
	v_mov_b32_e32 v36, v1
	v_cndmask_b32_e64 v35, 0, 32, vcc
	v_ldexp_f32 v34, v34, v35
	v_log_f32_e32 v34, v34
	v_cndmask_b32_e32 v35, 0, v250, vcc
	v_mov_b32_e32 v37, v1
	v_mov_b32_e32 v38, v1
	v_sub_f32_e32 v34, v34, v35
	v_floor_f32_e32 v34, v34
	v_cmp_gt_f32_e32 vcc, s12, v34
	v_mov_b32_e32 v39, v1
	s_nop 0
	v_cndmask_b32_e32 v35, 0, v251, vcc
	v_add_f32_e32 v34, v34, v35
	v_exp_f32_e32 v34, v34
	v_cndmask_b32_e32 v35, 0, v230, vcc
	v_ldexp_f32 v34, v34, v35
	v_mul_f32_e32 v30, v30, v34
	v_mul_f32_e32 v31, v31, v34
	v_mul_f32_e32 v26, v26, v34
	v_mul_f32_e32 v27, v27, v34
	v_mul_f32_e32 v22, v22, v34
	v_mul_f32_e32 v23, v23, v34
	v_mul_f32_e32 v18, v18, v34
	v_mul_f32_e32 v19, v19, v34
	v_cvt_pk_fp8_f32 v36, v30, v31
	v_cvt_pk_fp8_f32 v37, v26, v27
	v_cvt_pk_fp8_f32 v38, v22, v23
	v_cvt_pk_fp8_f32 v39, v18, v19
	v_mul_f32_e32 v32, v32, v34
	v_mul_f32_e32 v33, v33, v34
	v_mul_f32_e32 v28, v28, v34
	v_mul_f32_e32 v29, v29, v34
	v_mul_f32_e32 v22, v24, v34
	v_mul_f32_e32 v23, v25, v34
	v_mul_f32_e32 v18, v20, v34
	v_mul_f32_e32 v19, v21, v34
	v_cvt_pk_fp8_f32 v36, v32, v33 op_sel:[0,0,1]
	v_cvt_pk_fp8_f32 v37, v28, v29 op_sel:[0,0,1]
	v_cvt_pk_fp8_f32 v38, v22, v23 op_sel:[0,0,1]
	v_cvt_pk_fp8_f32 v39, v18, v19 op_sel:[0,0,1]
	v_or_b32_e32 v18, 2, v67
	v_lshlrev_b32_e32 v20, 7, v18
	v_mov_b32_e32 v21, v1
	v_lshl_add_u64 v[20:21], v[50:51], 0, v[20:21]
	v_lshl_add_u64 v[20:21], v[20:21], 0, v[0:1]
	global_store_dwordx4 v[20:21], v[36:39], off
	s_and_saveexec_b64 s[12:13], s[38:39]
	s_cbranch_execz .LBB0_1103
	v_div_scale_f32 v19, s[16:17], v34, v34, 1.0
	v_rcp_f32_e32 v20, v19
	v_div_scale_f32 v21, vcc, 1.0, v34, 1.0
	v_or_b32_e32 v18, v66, v18
	v_fma_f32 v22, -v19, v20, 1.0
	v_fmac_f32_e32 v20, v22, v20
	v_mul_f32_e32 v22, v21, v20
	v_fma_f32 v23, -v19, v22, v21
	v_fmac_f32_e32 v22, v23, v20
	v_fma_f32 v19, -v19, v22, v21
	v_div_fmas_f32 v19, v19, v20, v22
	v_div_fixup_f32 v20, v19, v34, 1.0
	v_ashrrev_i32_e32 v19, 31, v18
	v_lshl_add_u64 v[18:19], v[18:19], 2, s[8:9]
	global_store_dword v[18:19], v20, off
; DEV void phase_prep(const Params& p, char* smem) {
;     ...
;       for (int r = 0; r < 4; r++) {
;         float mx = 0.f;
; #pragma unroll
;         for (int q = 0; q < 4; q++) mx = fmaxf(mx, fmaxf(fmaxf(fabsf(v[r][q].x), fabsf(v[r][q].y)), fmaxf(fabsf(v[r][q].z), fabsf(v[r][q].w))));
; #pragma unroll
;         for (int o = 32; o > 0; o >>= 1) mx = fmaxf(mx, __shfl_xor(mx, o));
;         mx = fmaxf(mx, 1e-30f);
;         const float sc = exp2f(floorf(log2f(384.f / mx)));
;         unsigned ow[4];
; #pragma unroll
;         for (int q = 0; q < 4; q++) {
;           int t = __builtin_amdgcn_cvt_pk_fp8_f32(v[r][q].x * sc, v[r][q].y * sc, 0, false);
;           t = __builtin_amdgcn_cvt_pk_fp8_f32(v[r][q].z * sc, v[r][q].w * sc, t, true);
;           ow[q] = (unsigned)t;
;         }
;         const int row = rowb + r; const int l = row >> 14, e = row & 16383;
;         unsigned char* dst = isv ? (l ? WSP(unsigned char, OFF_V1) : WSP(unsigned char, OFF_V0)) : (l ? WSP(unsigned char, OFF_U1) : WSP(unsigned char, OFF_U0));
;         *(uint4*)(dst + (size_t)e * 1024 + lane * 16) = make_uint4(ow[0], ow[1], ow[2], ow[3]);
;         if (lane == 0) WSP(float, S_UVSC)[(l * 2 + isv) * 16384 + e] = 1.f / sc;
.LBB0_1103:
	s_or_b64 exec, exec, s[12:13]
	s_waitcnt vmcnt(6)
	v_max_f32_e64 v18, |v17|, |v17|
	v_max_f32_e64 v19, |v16|, |v16|
	v_max_f32_e32 v18, v19, v18
	s_waitcnt vmcnt(3)
	v_max_f32_e64 v19, |v13|, |v13|
	v_max_f32_e64 v20, |v12|, |v12|
	v_max_f32_e32 v19, v20, v19
	v_max3_f32 v18, |v14|, |v15|, v18
	v_max3_f32 v19, |v10|, |v11|, v19
	v_max3_f32 v18, v18, 0, v19
	v_max_f32_e64 v19, |v9|, |v9|
	v_max_f32_e64 v20, |v8|, |v8|
	v_max_f32_e32 v19, v20, v19
	v_max_f32_e64 v20, |v5|, |v5|
	v_max_f32_e64 v21, |v4|, |v4|
	v_max_f32_e32 v20, v21, v20
	v_max3_f32 v19, |v6|, |v7|, v19
	v_max3_f32 v20, |v2|, |v3|, v20
	v_max3_f32 v18, v18, v19, v20
	ds_bpermute_b32 v19, v68, v18
	s_mov_b32 s12, 0xda24260
	s_mov_b32 s16, 0x43c00000
	s_waitcnt lgkmcnt(0)
	v_max_f32_e32 v19, v19, v19
	v_max_f32_e32 v18, v18, v19
	ds_bpermute_b32 v19, v69, v18
	s_waitcnt lgkmcnt(0)
	v_max_f32_e32 v19, v19, v19
	v_max_f32_e32 v18, v18, v19
	ds_bpermute_b32 v19, v70, v18
	s_waitcnt lgkmcnt(0)
	v_max_f32_e32 v19, v19, v19
	v_max_f32_e32 v18, v18, v19
	ds_bpermute_b32 v19, v71, v18
	s_waitcnt lgkmcnt(0)
	v_max_f32_e32 v19, v19, v19
	v_max_f32_e32 v18, v18, v19
	ds_bpermute_b32 v19, v72, v18
	s_waitcnt lgkmcnt(0)
	v_max_f32_e32 v19, v19, v19
	v_max_f32_e32 v18, v18, v19
	ds_bpermute_b32 v19, v73, v18
	s_waitcnt lgkmcnt(0)
	v_max3_f32 v18, v18, v19, s12
	v_div_scale_f32 v19, s[12:13], v18, v18, s16
	v_rcp_f32_e32 v20, v19
	v_div_scale_f32 v21, vcc, s16, v18, s16
	s_mov_b32 s12, 0x800000
	v_fma_f32 v22, -v19, v20, 1.0
	v_fmac_f32_e32 v20, v22, v20
	v_mul_f32_e32 v22, v21, v20
	v_fma_f32 v23, -v19, v22, v21
	v_fmac_f32_e32 v22, v23, v20
	v_fma_f32 v19, -v19, v22, v21
	v_div_fmas_f32 v19, v19, v20, v22
	v_div_fixup_f32 v18, v19, v18, s16
	v_cmp_gt_f32_e32 vcc, s12, v18
	s_mov_b32 s12, 0xc2fc0000
	v_mov_b32_e32 v20, v1
	v_cndmask_b32_e64 v19, 0, 32, vcc
	v_ldexp_f32 v18, v18, v19
	v_log_f32_e32 v18, v18
	v_cndmask_b32_e32 v19, 0, v250, vcc
	v_mov_b32_e32 v21, v1
	v_mov_b32_e32 v22, v1
	v_sub_f32_e32 v18, v18, v19
	v_floor_f32_e32 v18, v18
	v_cmp_gt_f32_e32 vcc, s12, v18
	v_mov_b32_e32 v23, v1
	s_nop 0
	v_cndmask_b32_e32 v19, 0, v251, vcc
	v_add_f32_e32 v18, v18, v19
	v_exp_f32_e32 v18, v18
	v_cndmask_b32_e32 v19, 0, v230, vcc
	v_ldexp_f32 v18, v18, v19
	v_mul_f32_e32 v14, v14, v18
	v_mul_f32_e32 v15, v15, v18
	v_mul_f32_e32 v10, v10, v18
	v_mul_f32_e32 v11, v11, v18
	v_mul_f32_e32 v6, v6, v18
	v_mul_f32_e32 v7, v7, v18
	v_mul_f32_e32 v2, v2, v18
	v_mul_f32_e32 v3, v3, v18
	v_cvt_pk_fp8_f32 v20, v14, v15
	v_cvt_pk_fp8_f32 v21, v10, v11
	v_cvt_pk_fp8_f32 v22, v6, v7
	v_cvt_pk_fp8_f32 v23, v2, v3
	v_mul_f32_e32 v16, v16, v18
	v_mul_f32_e32 v17, v17, v18
	v_mul_f32_e32 v12, v12, v18
	v_mul_f32_e32 v13, v13, v18
	v_mul_f32_e32 v6, v8, v18
	v_mul_f32_e32 v7, v9, v18
	v_mul_f32_e32 v2, v4, v18
	v_mul_f32_e32 v3, v5, v18
	v_cvt_pk_fp8_f32 v20, v16, v17 op_sel:[0,0,1]
	v_cvt_pk_fp8_f32 v21, v12, v13 op_sel:[0,0,1]
	v_cvt_pk_fp8_f32 v22, v6, v7 op_sel:[0,0,1]
	v_cvt_pk_fp8_f32 v23, v2, v3 op_sel:[0,0,1]
	v_or_b32_e32 v2, 3, v67
	v_lshlrev_b32_e32 v4, 7, v2
	v_mov_b32_e32 v5, v1
	v_lshl_add_u64 v[4:5], v[50:51], 0, v[4:5]
	v_lshl_add_u64 v[4:5], v[4:5], 0, v[0:1]
	global_store_dwordx4 v[4:5], v[20:23], off
	s_and_saveexec_b64 s[12:13], s[38:39]
	s_cbranch_execz .LBB0_1105
	v_div_scale_f32 v0, s[16:17], v18, v18, 1.0
	v_rcp_f32_e32 v3, v0
	v_div_scale_f32 v4, vcc, 1.0, v18, 1.0
	v_or_b32_e32 v2, v66, v2
	v_fma_f32 v5, -v0, v3, 1.0
	v_fmac_f32_e32 v3, v5, v3
	v_mul_f32_e32 v5, v4, v3
	v_fma_f32 v6, -v0, v5, v4
	v_fmac_f32_e32 v5, v6, v3
	v_fma_f32 v0, -v0, v5, v4
	v_div_fmas_f32 v0, v0, v3, v5
	v_ashrrev_i32_e32 v3, 31, v2
	v_div_fixup_f32 v0, v0, v18, 1.0
	v_lshl_add_u64 v[2:3], v[2:3], 2, s[8:9]
	global_store_dword v[2:3], v0, off

; DEV unsigned xb_add(unsigned* p, unsigned v) { return __hip_atomic_fetch_add(p, v, __ATOMIC_RELAXED, __HIP_MEMORY_SCOPE_AGENT); }
; DEV void xcd_barrier(const XcdBarrier& b) {
;   asm volatile("s_waitcnt vmcnt(0)" ::: "memory");
;   __syncthreads();
;   if (threadIdx.x == 0) {
;     unsigned* bar = b.bar;
;     __builtin_amdgcn_s_waitcnt(0);
;     unsigned nloc = b.st[0], nx = b.st[1];
;     if (nloc == 0u) { xcd_barrier_complete(bar, b.x, nloc, nx); b.st[0] = nloc; b.st[1] = nx; }
;     const unsigned old = xb_add(&bar[XB_XSUB(b.x)], 1u);
.Lpeer_grid_barrier:
	s_waitcnt vmcnt(0)
	s_waitcnt lgkmcnt(0)
	s_barrier
	s_and_saveexec_b64 s[0:1], s[90:91]
	s_cbranch_execz .LBB0_1193
	s_waitcnt vmcnt(0) expcnt(0) lgkmcnt(0)
	ds_read_b32 v3, v197
	ds_read_b32 v2, v198
	s_waitcnt lgkmcnt(1)
	v_cmp_ne_u32_e32 vcc, 0, v3
	s_cbranch_vccnz .LBB0_1157
	s_mov_b32 s10, 1
	s_branch .LBB0_1145
